# v9 + row-statistics miss path touches all 8 rows lines first (A, H epilogues) + attention epilogue lane^1 exchange by DPP quad_perm instead of ds_bpermute round trips
# baseline (speedup 1.0000x reference)
.LBB0_140:
	v_mov_b32_e32 v130, s77
	ds_read_b32 v130, v130
	s_add_i32 s0, s24, 1
	s_lshl_b32 s20, s24, 8
	s_or_b32 s16, s0, s69
	v_add_u32_e32 v172, s20, v193
	s_waitcnt lgkmcnt(0)
	v_readfirstlane_b32 s0, v130
	s_cmp_eq_u32 s0, s16
	s_mov_b64 s[0:1], -1
	s_mov_b32 s33, 0xf800000
	s_cbranch_scc1 .LBB0_142
	v_and_b32_e32 v131, 64, v231
	v_xor_b32_e32 v130, 16, v231
	v_add_u32_e32 v131, 64, v131
	v_cmp_lt_i32_e32 vcc, v130, v131
	v_ashrrev_i32_e32 v173, 31, v172
	s_nop 0
	v_cndmask_b32_e32 v130, v231, v130, vcc
	v_lshlrev_b32_e32 v141, 2, v130
	v_xor_b32_e32 v130, 32, v231
	v_cmp_lt_i32_e32 vcc, v130, v131
	s_nop 1
	v_cndmask_b32_e32 v130, v231, v130, vcc
	v_lshlrev_b32_e32 v140, 2, v130
	v_lshlrev_b64 v[130:131], 7, v[172:173]
	v_lshl_add_u64 v[132:133], v[166:167], 0, v[130:131]
	s_mov_b64 s[0:1], 0x1000
	global_load_dword v184, v[132:133], off offset:2048
	v_lshl_add_u64 v[194:195], v[132:133], 0, s[0:1]
	global_load_dword v185, v[194:195], off
	global_load_dword v186, v[194:195], off offset:2048
	s_mov_b64 s[0:1], 0x4000
	v_lshl_add_u64 v[194:195], v[132:133], 0, s[0:1]
	global_load_dword v187, v[194:195], off
	global_load_dword v188, v[194:195], off offset:2048
	s_mov_b64 s[0:1], 0x5000
	v_lshl_add_u64 v[194:195], v[132:133], 0, s[0:1]
	global_load_dword v189, v[194:195], off
	global_load_dword v190, v[194:195], off offset:2048
	global_load_dwordx4 v[134:137], v[132:133], off
	global_load_dwordx4 v[142:145], v[132:133], off offset:16
	s_waitcnt vmcnt(0)
	v_mov_b32_e32 v130, v134
	v_mov_b32_e32 v131, v142
	v_mov_b32_e32 v142, v135
	v_mov_b32_e32 v134, v136
	v_mov_b32_e32 v135, v144
	v_mov_b32_e32 v144, v137
	v_pk_add_f32 v[130:131], v[130:131], v[142:143]
	v_pk_add_f32 v[134:135], v[134:135], v[144:145]
	s_nop 0
	v_pk_add_f32 v[130:131], v[130:131], v[134:135]
	s_nop 0
	v_add_f32_e32 v130, v130, v131
	ds_bpermute_b32 v131, v141, v130
	s_waitcnt lgkmcnt(0)
	v_add_f32_e32 v130, v130, v131
	ds_bpermute_b32 v131, v140, v130
	s_waitcnt lgkmcnt(0)
	v_add_f32_e32 v130, v130, v131
	v_fmamk_f32 v130, v130, 0x3a000000, v230
	v_cmp_gt_f32_e32 vcc, s33, v130
	v_mul_f32_e32 v131, 0x4f800000, v130
	s_nop 0
	v_cndmask_b32_e32 v130, v130, v131, vcc
	v_sqrt_f32_e32 v131, v130
	s_nop 0
	v_add_u32_e32 v134, -1, v131
	v_fma_f32 v135, -v134, v131, v130
	v_cmp_ge_f32_e64 s[0:1], 0, v135
	v_add_u32_e32 v135, 1, v131
	s_nop 0
	v_cndmask_b32_e64 v134, v131, v134, s[0:1]
	v_fma_f32 v131, -v135, v131, v130
	v_cmp_lt_f32_e64 s[0:1], 0, v131
	s_nop 1
	v_cndmask_b32_e64 v131, v134, v135, s[0:1]
	v_mul_f32_e32 v134, 0x37800000, v131
	v_cndmask_b32_e32 v131, v131, v134, vcc
	v_cmp_class_f32_e32 vcc, v130, v228
	s_nop 1
	v_cndmask_b32_e32 v138, v131, v130, vcc
	v_or_b32_e32 v130, 16, v172
	v_ashrrev_i32_e32 v131, 31, v130
	v_lshlrev_b64 v[130:131], 7, v[130:131]
	v_lshl_add_u64 v[130:131], v[166:167], 0, v[130:131]
	global_load_dwordx4 v[134:137], v[130:131], off
	global_load_dwordx4 v[142:145], v[130:131], off offset:16
	s_waitcnt vmcnt(1)
	v_mov_b32_e32 v130, v134
	s_waitcnt vmcnt(0)
	v_mov_b32_e32 v131, v142
	v_mov_b32_e32 v142, v135
	v_mov_b32_e32 v134, v136
	v_mov_b32_e32 v135, v144
	v_mov_b32_e32 v144, v137
	v_pk_add_f32 v[130:131], v[130:131], v[142:143]
	v_pk_add_f32 v[134:135], v[134:135], v[144:145]
	s_nop 0
	v_pk_add_f32 v[130:131], v[130:131], v[134:135]
	s_nop 0
	v_add_f32_e32 v130, v130, v131
	ds_bpermute_b32 v131, v141, v130
	s_waitcnt lgkmcnt(0)
	v_add_f32_e32 v130, v130, v131
	ds_bpermute_b32 v131, v140, v130
	s_waitcnt lgkmcnt(0)
	v_add_f32_e32 v130, v130, v131
	v_fmamk_f32 v130, v130, 0x3a000000, v230
	v_cmp_gt_f32_e32 vcc, s33, v130
	v_mul_f32_e32 v131, 0x4f800000, v130
	s_nop 0
	v_cndmask_b32_e32 v130, v130, v131, vcc
	v_sqrt_f32_e32 v131, v130
	s_nop 0
	v_add_u32_e32 v134, -1, v131
	v_fma_f32 v135, -v134, v131, v130
	v_cmp_ge_f32_e64 s[0:1], 0, v135
	v_add_u32_e32 v135, 1, v131
	s_nop 0
	v_cndmask_b32_e64 v134, v131, v134, s[0:1]
	v_fma_f32 v131, -v135, v131, v130
	v_cmp_lt_f32_e64 s[0:1], 0, v131
	s_nop 1
	v_cndmask_b32_e64 v131, v134, v135, s[0:1]
	v_mul_f32_e32 v134, 0x37800000, v131
	v_cndmask_b32_e32 v131, v131, v134, vcc
	v_cmp_class_f32_e32 vcc, v130, v228
	s_nop 1
	v_cndmask_b32_e32 v130, v131, v130, vcc
	v_div_scale_f32 v131, s[0:1], v130, v130, 1.0
	v_rcp_f32_e32 v134, v131
	s_nop 0
	v_fma_f32 v135, -v131, v134, 1.0
	v_fmac_f32_e32 v134, v135, v134
	v_div_scale_f32 v135, vcc, 1.0, v130, 1.0
	v_mul_f32_e32 v136, v135, v134
	v_fma_f32 v137, -v131, v136, v135
	v_fmac_f32_e32 v136, v137, v134
	v_fma_f32 v131, -v131, v136, v135
	v_div_fmas_f32 v131, v131, v134, v136
	v_div_fixup_f32 v175, v131, v130, 1.0
	v_div_scale_f32 v130, s[0:1], v138, v138, 1.0
	v_rcp_f32_e32 v131, v130
	s_nop 0
	v_fma_f32 v134, -v130, v131, 1.0
	v_fmac_f32_e32 v131, v134, v131
	v_div_scale_f32 v134, vcc, 1.0, v138, 1.0
	v_mul_f32_e32 v135, v134, v131
	v_fma_f32 v136, -v130, v135, v134
	v_fmac_f32_e32 v135, v136, v131
	v_fma_f32 v130, -v130, v135, v134
	v_div_fmas_f32 v130, v130, v131, v135
	v_div_fixup_f32 v174, v130, v138, 1.0
	v_or_b32_e32 v130, 32, v172
	v_ashrrev_i32_e32 v131, 31, v130
	v_lshlrev_b64 v[130:131], 7, v[130:131]
	ds_write2_b32 v192, v174, v175 offset1:16
	v_lshl_add_u64 v[130:131], v[166:167], 0, v[130:131]
	global_load_dwordx4 v[134:137], v[130:131], off
	global_load_dwordx4 v[142:145], v[130:131], off offset:16
	s_waitcnt vmcnt(1)
	v_mov_b32_e32 v130, v134
	s_waitcnt vmcnt(0)
	v_mov_b32_e32 v131, v142
	v_mov_b32_e32 v142, v135
	v_mov_b32_e32 v134, v136
	v_mov_b32_e32 v135, v144
	v_mov_b32_e32 v144, v137
	v_pk_add_f32 v[130:131], v[130:131], v[142:143]
	v_pk_add_f32 v[134:135], v[134:135], v[144:145]
	s_nop 0
	v_pk_add_f32 v[130:131], v[130:131], v[134:135]
	s_nop 0
	v_add_f32_e32 v130, v130, v131
	ds_bpermute_b32 v131, v141, v130
	s_waitcnt lgkmcnt(0)
	v_add_f32_e32 v130, v130, v131
	ds_bpermute_b32 v131, v140, v130
	s_waitcnt lgkmcnt(0)
	v_add_f32_e32 v130, v130, v131
	v_fmamk_f32 v130, v130, 0x3a000000, v230
	v_cmp_gt_f32_e32 vcc, s33, v130
	v_mul_f32_e32 v131, 0x4f800000, v130
	s_nop 0
	v_cndmask_b32_e32 v130, v130, v131, vcc
	v_sqrt_f32_e32 v131, v130
	s_nop 0
	v_add_u32_e32 v134, -1, v131
	v_fma_f32 v135, -v134, v131, v130
	v_cmp_ge_f32_e64 s[0:1], 0, v135
	v_add_u32_e32 v135, 1, v131
	s_nop 0
	v_cndmask_b32_e64 v134, v131, v134, s[0:1]
	v_fma_f32 v131, -v135, v131, v130
	v_cmp_lt_f32_e64 s[0:1], 0, v131
	s_nop 1
	v_cndmask_b32_e64 v131, v134, v135, s[0:1]
	v_mul_f32_e32 v134, 0x37800000, v131
	v_cndmask_b32_e32 v131, v131, v134, vcc
	v_cmp_class_f32_e32 vcc, v130, v228
	s_nop 1
	v_cndmask_b32_e32 v138, v131, v130, vcc
	v_or_b32_e32 v130, 48, v172
	v_ashrrev_i32_e32 v131, 31, v130
	v_lshlrev_b64 v[130:131], 7, v[130:131]
	v_lshl_add_u64 v[130:131], v[166:167], 0, v[130:131]
	global_load_dwordx4 v[134:137], v[130:131], off
	global_load_dwordx4 v[142:145], v[130:131], off offset:16
	s_waitcnt vmcnt(1)
	v_mov_b32_e32 v130, v134
	s_waitcnt vmcnt(0)
	v_mov_b32_e32 v131, v142
	v_mov_b32_e32 v142, v135
	v_mov_b32_e32 v134, v136
	v_mov_b32_e32 v135, v144
	v_mov_b32_e32 v144, v137
	v_pk_add_f32 v[130:131], v[130:131], v[142:143]
	v_pk_add_f32 v[134:135], v[134:135], v[144:145]
	s_nop 0
	v_pk_add_f32 v[130:131], v[130:131], v[134:135]
	s_nop 0
	v_add_f32_e32 v130, v130, v131
	ds_bpermute_b32 v131, v141, v130
	s_waitcnt lgkmcnt(0)
	v_add_f32_e32 v130, v130, v131
	ds_bpermute_b32 v131, v140, v130
	s_waitcnt lgkmcnt(0)
	v_add_f32_e32 v130, v130, v131
	v_fmamk_f32 v130, v130, 0x3a000000, v230
	v_cmp_gt_f32_e32 vcc, s33, v130
	v_mul_f32_e32 v131, 0x4f800000, v130
	s_nop 0
	v_cndmask_b32_e32 v130, v130, v131, vcc
	v_sqrt_f32_e32 v131, v130
	s_nop 0
	v_add_u32_e32 v134, -1, v131
	v_fma_f32 v135, -v134, v131, v130
	v_cmp_ge_f32_e64 s[0:1], 0, v135
	v_add_u32_e32 v135, 1, v131
	s_nop 0
	v_cndmask_b32_e64 v134, v131, v134, s[0:1]
	v_fma_f32 v131, -v135, v131, v130
	v_cmp_lt_f32_e64 s[0:1], 0, v131
	s_nop 1
	v_cndmask_b32_e64 v131, v134, v135, s[0:1]
	v_mul_f32_e32 v134, 0x37800000, v131
	v_cndmask_b32_e32 v131, v131, v134, vcc
	v_cmp_class_f32_e32 vcc, v130, v228
	s_nop 1
	v_cndmask_b32_e32 v130, v131, v130, vcc
	v_div_scale_f32 v131, s[0:1], v130, v130, 1.0
	v_rcp_f32_e32 v134, v131
	s_nop 0
	v_fma_f32 v135, -v131, v134, 1.0
	v_fmac_f32_e32 v134, v135, v134
	v_div_scale_f32 v135, vcc, 1.0, v130, 1.0
	v_mul_f32_e32 v136, v135, v134
	v_fma_f32 v137, -v131, v136, v135
	v_fmac_f32_e32 v136, v137, v134
	v_fma_f32 v131, -v131, v136, v135
	v_div_fmas_f32 v131, v131, v134, v136
	v_div_fixup_f32 v177, v131, v130, 1.0
	v_div_scale_f32 v130, s[0:1], v138, v138, 1.0
	v_rcp_f32_e32 v131, v130
	s_mov_b64 s[0:1], 0x4000
	v_lshl_add_u64 v[142:143], v[132:133], 0, s[0:1]
	s_movk_i32 s0, 0x4000
	v_fma_f32 v134, -v130, v131, 1.0
	v_fmac_f32_e32 v131, v134, v131
	v_div_scale_f32 v134, vcc, 1.0, v138, 1.0
	v_mul_f32_e32 v135, v134, v131
	v_fma_f32 v136, -v130, v135, v134
	v_fmac_f32_e32 v135, v136, v131
	v_fma_f32 v130, -v130, v135, v134
	v_div_fmas_f32 v130, v130, v131, v135
	v_div_fixup_f32 v176, v130, v138, 1.0
	v_add_co_u32_e32 v130, vcc, s0, v132
	s_movk_i32 s0, 0x5000
	s_nop 0
	v_addc_co_u32_e32 v131, vcc, 0, v133, vcc
	v_add_co_u32_e32 v134, vcc, s0, v132
	ds_write2_b32 v192, v176, v177 offset0:32 offset1:48
	s_nop 0
	v_addc_co_u32_e32 v135, vcc, 0, v133, vcc
	global_load_dwordx4 v[136:139], v[134:135], off offset:-4096
	s_nop 0
	global_load_dwordx4 v[142:145], v[142:143], off offset:16
	s_waitcnt vmcnt(1)
	v_mov_b32_e32 v146, v136
	s_waitcnt vmcnt(0)
	v_mov_b32_e32 v147, v142
	v_mov_b32_e32 v142, v137
	v_pk_add_f32 v[136:137], v[146:147], v[142:143]
	v_mov_b32_e32 v142, v138
	v_mov_b32_e32 v143, v144
	v_mov_b32_e32 v144, v139
	v_pk_add_f32 v[138:139], v[142:143], v[144:145]
	s_nop 0
	v_pk_add_f32 v[136:137], v[136:137], v[138:139]
	s_nop 0
	v_add_f32_e32 v136, v136, v137
	ds_bpermute_b32 v137, v141, v136
	s_waitcnt lgkmcnt(0)
	v_add_f32_e32 v136, v136, v137
	ds_bpermute_b32 v137, v140, v136
	s_waitcnt lgkmcnt(0)
	v_add_f32_e32 v136, v136, v137
	v_fmamk_f32 v136, v136, 0x3a000000, v230
	v_cmp_gt_f32_e32 vcc, s33, v136
	v_mul_f32_e32 v137, 0x4f800000, v136
	s_nop 0
	v_cndmask_b32_e32 v136, v136, v137, vcc
	v_sqrt_f32_e32 v137, v136
	s_nop 0
	v_add_u32_e32 v138, -1, v137
	v_fma_f32 v139, -v138, v137, v136
	v_cmp_ge_f32_e64 s[0:1], 0, v139
	v_add_u32_e32 v139, 1, v137
	s_nop 0
	v_cndmask_b32_e64 v138, v137, v138, s[0:1]
	v_fma_f32 v137, -v139, v137, v136
	v_cmp_lt_f32_e64 s[0:1], 0, v137
	s_nop 1
	v_cndmask_b32_e64 v137, v138, v139, s[0:1]
	v_mul_f32_e32 v138, 0x37800000, v137
	s_mov_b64 s[0:1], 0x4800
	v_cndmask_b32_e32 v137, v137, v138, vcc
	v_cmp_class_f32_e32 vcc, v136, v228
	v_lshl_add_u64 v[142:143], v[132:133], 0, s[0:1]
	s_nop 0
	v_cndmask_b32_e32 v146, v137, v136, vcc
	global_load_dwordx4 v[136:139], v[130:131], off offset:2048
	s_nop 0
	global_load_dwordx4 v[142:145], v[142:143], off offset:16
	s_waitcnt vmcnt(1)
	v_mov_b32_e32 v130, v136
	s_waitcnt vmcnt(0)
	v_mov_b32_e32 v131, v142
	v_mov_b32_e32 v142, v137
	v_mov_b32_e32 v136, v138
	v_mov_b32_e32 v137, v144
	v_mov_b32_e32 v144, v139
	v_pk_add_f32 v[130:131], v[130:131], v[142:143]
	v_pk_add_f32 v[136:137], v[136:137], v[144:145]
	s_nop 0
	v_pk_add_f32 v[130:131], v[130:131], v[136:137]
	s_nop 0
	v_add_f32_e32 v130, v130, v131
	ds_bpermute_b32 v131, v141, v130
	s_waitcnt lgkmcnt(0)
	v_add_f32_e32 v130, v130, v131
	ds_bpermute_b32 v131, v140, v130
	s_waitcnt lgkmcnt(0)
	v_add_f32_e32 v130, v130, v131
	v_fmamk_f32 v130, v130, 0x3a000000, v230
	v_cmp_gt_f32_e32 vcc, s33, v130
	v_mul_f32_e32 v131, 0x4f800000, v130
	s_nop 0
	v_cndmask_b32_e32 v130, v130, v131, vcc
	v_sqrt_f32_e32 v131, v130
	s_nop 0
	v_add_u32_e32 v136, -1, v131
	v_fma_f32 v137, -v136, v131, v130
	v_cmp_ge_f32_e64 s[0:1], 0, v137
	v_add_u32_e32 v137, 1, v131
	s_nop 0
	v_cndmask_b32_e64 v136, v131, v136, s[0:1]
	v_fma_f32 v131, -v137, v131, v130
	v_cmp_lt_f32_e64 s[0:1], 0, v131
	s_nop 1
	v_cndmask_b32_e64 v131, v136, v137, s[0:1]
	v_mul_f32_e32 v136, 0x37800000, v131
	v_cndmask_b32_e32 v131, v131, v136, vcc
	v_cmp_class_f32_e32 vcc, v130, v228
	s_nop 1
	v_cndmask_b32_e32 v130, v131, v130, vcc
	v_div_scale_f32 v131, s[0:1], v130, v130, 1.0
	v_rcp_f32_e32 v136, v131
	s_nop 0
	v_fma_f32 v137, -v131, v136, 1.0
	v_fmac_f32_e32 v136, v137, v136
	v_div_scale_f32 v137, vcc, 1.0, v130, 1.0
	v_mul_f32_e32 v138, v137, v136
	v_fma_f32 v139, -v131, v138, v137
	v_fmac_f32_e32 v138, v139, v136
	v_fma_f32 v131, -v131, v138, v137
	v_div_fmas_f32 v131, v131, v136, v138
	v_div_fixup_f32 v131, v131, v130, 1.0
	v_div_scale_f32 v130, s[0:1], v146, v146, 1.0
	v_rcp_f32_e32 v136, v130
	s_mov_b64 s[0:1], 0x5000
	v_lshl_add_u64 v[142:143], v[132:133], 0, s[0:1]
	v_mov_b32_e32 v182, v131
	v_fma_f32 v137, -v130, v136, 1.0
	v_fmac_f32_e32 v136, v137, v136
	v_div_scale_f32 v137, vcc, 1.0, v146, 1.0
	v_mul_f32_e32 v138, v137, v136
	v_fma_f32 v139, -v130, v138, v137
	v_fmac_f32_e32 v138, v139, v136
	v_fma_f32 v130, -v130, v138, v137
	v_div_fmas_f32 v130, v130, v136, v138
	v_div_fixup_f32 v130, v130, v146, 1.0
	ds_write2_b32 v192, v130, v131 offset0:64 offset1:80
	global_load_dwordx4 v[136:139], v[134:135], off
	s_nop 0
	global_load_dwordx4 v[142:145], v[142:143], off offset:16
	s_waitcnt vmcnt(1)
	v_mov_b32_e32 v146, v136
	s_waitcnt vmcnt(0)
	v_mov_b32_e32 v147, v142
	v_mov_b32_e32 v142, v137
	v_pk_add_f32 v[136:137], v[146:147], v[142:143]
	v_mov_b32_e32 v142, v138
	v_mov_b32_e32 v143, v144
	v_mov_b32_e32 v144, v139
	v_pk_add_f32 v[138:139], v[142:143], v[144:145]
	s_nop 0
	v_pk_add_f32 v[136:137], v[136:137], v[138:139]
	s_nop 0
	v_add_f32_e32 v136, v136, v137
	ds_bpermute_b32 v137, v141, v136
	s_waitcnt lgkmcnt(0)
	v_add_f32_e32 v136, v136, v137
	ds_bpermute_b32 v137, v140, v136
	s_waitcnt lgkmcnt(0)
	v_add_f32_e32 v136, v136, v137
	v_fmamk_f32 v136, v136, 0x3a000000, v230
	v_cmp_gt_f32_e32 vcc, s33, v136
	v_mul_f32_e32 v137, 0x4f800000, v136
	s_nop 0
	v_cndmask_b32_e32 v136, v136, v137, vcc
	v_sqrt_f32_e32 v137, v136
	s_nop 0
	v_add_u32_e32 v138, -1, v137
	v_fma_f32 v139, -v138, v137, v136
	v_cmp_ge_f32_e64 s[0:1], 0, v139
	v_add_u32_e32 v139, 1, v137
	s_nop 0
	v_cndmask_b32_e64 v138, v137, v138, s[0:1]
	v_fma_f32 v137, -v139, v137, v136
	v_cmp_lt_f32_e64 s[0:1], 0, v137
	s_nop 1
	v_cndmask_b32_e64 v137, v138, v139, s[0:1]
	v_mul_f32_e32 v138, 0x37800000, v137
	v_cndmask_b32_e32 v137, v137, v138, vcc
	v_cmp_class_f32_e32 vcc, v136, v228
	s_mov_b64 s[0:1], 0x5800
	s_nop 0
	v_cndmask_b32_e32 v142, v137, v136, vcc
	v_lshl_add_u64 v[136:137], v[132:133], 0, s[0:1]
	global_load_dwordx4 v[132:135], v[134:135], off offset:2048
	s_nop 0
	global_load_dwordx4 v[136:139], v[136:137], off offset:16
	s_waitcnt vmcnt(1)
	v_mov_b32_e32 v144, v132
	s_waitcnt vmcnt(0)
	v_mov_b32_e32 v145, v136
	v_mov_b32_e32 v136, v133
	v_pk_add_f32 v[132:133], v[144:145], v[136:137]
	v_mov_b32_e32 v136, v134
	v_mov_b32_e32 v137, v138
	v_mov_b32_e32 v138, v135
	v_pk_add_f32 v[134:135], v[136:137], v[138:139]
	s_nop 0
	v_pk_add_f32 v[132:133], v[132:133], v[134:135]
	s_nop 0
	v_add_f32_e32 v132, v132, v133
	ds_bpermute_b32 v133, v141, v132
	s_waitcnt lgkmcnt(0)
	v_add_f32_e32 v132, v132, v133
	ds_bpermute_b32 v133, v140, v132
	s_waitcnt lgkmcnt(0)
	v_add_f32_e32 v132, v132, v133
	v_fmamk_f32 v132, v132, 0x3a000000, v230
	v_cmp_gt_f32_e32 vcc, s33, v132
	v_mul_f32_e32 v133, 0x4f800000, v132
	s_nop 0
	v_cndmask_b32_e32 v132, v132, v133, vcc
	v_sqrt_f32_e32 v133, v132
	s_nop 0
	v_add_u32_e32 v134, -1, v133
	v_fma_f32 v135, -v134, v133, v132
	v_cmp_ge_f32_e64 s[0:1], 0, v135
	v_add_u32_e32 v135, 1, v133
	s_nop 0
	v_cndmask_b32_e64 v134, v133, v134, s[0:1]
	v_fma_f32 v133, -v135, v133, v132
	v_cmp_lt_f32_e64 s[0:1], 0, v133
	s_nop 1
	v_cndmask_b32_e64 v133, v134, v135, s[0:1]
	v_mul_f32_e32 v134, 0x37800000, v133
	v_cndmask_b32_e32 v133, v133, v134, vcc
	v_cmp_class_f32_e32 vcc, v132, v228
	s_nop 1
	v_cndmask_b32_e32 v132, v133, v132, vcc
	v_div_scale_f32 v133, s[0:1], v132, v132, 1.0
	v_rcp_f32_e32 v134, v133
	s_nop 0
	v_fma_f32 v135, -v133, v134, 1.0
	v_fmac_f32_e32 v134, v135, v134
	v_div_scale_f32 v135, vcc, 1.0, v132, 1.0
	v_mul_f32_e32 v136, v135, v134
	v_fma_f32 v137, -v133, v136, v135
	v_fmac_f32_e32 v136, v137, v134
	v_fma_f32 v133, -v133, v136, v135
	v_div_fmas_f32 v133, v133, v134, v136
	v_div_fixup_f32 v133, v133, v132, 1.0
	v_div_scale_f32 v132, s[0:1], v142, v142, 1.0
	v_rcp_f32_e32 v134, v132
	s_mov_b64 s[0:1], 0
	v_mov_b32_e32 v178, v133
	v_fma_f32 v135, -v132, v134, 1.0
	v_fmac_f32_e32 v134, v135, v134
	v_div_scale_f32 v135, vcc, 1.0, v142, 1.0
	v_mul_f32_e32 v136, v135, v134
	v_fma_f32 v137, -v132, v136, v135
	v_fmac_f32_e32 v136, v137, v134
	v_fma_f32 v132, -v132, v136, v135
	v_div_fmas_f32 v132, v132, v134, v136
	v_div_fixup_f32 v132, v132, v142, 1.0
	v_mov_b32_e32 v134, s77
	v_mov_b32_e32 v135, s16
	v_mov_b32_e32 v180, v132
	ds_write2_b32 v192, v132, v133 offset0:96 offset1:112
	ds_write_b32 v134, v135

.LBB0_943:
	s_or_b64 exec, exec, s[0:1]
	s_waitcnt lgkmcnt(3)
	v_div_scale_f32 v0, s[2:3], v80, v80, 1.0
	v_rcp_f32_e32 v14, v0
	s_lshl_b32 s0, s84, 8
	s_add_u32 s0, s6, s0
	s_addc_u32 s1, s7, 0
	v_fma_f32 v15, -v0, v14, 1.0
	v_fmac_f32_e32 v14, v15, v14
	v_div_scale_f32 v15, vcc, 1.0, v80, 1.0
	v_mul_f32_e32 v84, v15, v14
	v_fma_f32 v85, -v0, v84, v15
	v_fmac_f32_e32 v84, v85, v14
	v_fma_f32 v0, -v0, v84, v15
	v_div_fmas_f32 v0, v0, v14, v84
	v_and_b32_e32 v14, 64, v231
	v_div_fixup_f32 v86, v0, v80, 1.0
	v_xor_b32_e32 v0, 1, v231
	v_add_u32_e32 v14, 64, v14
	v_cmp_lt_i32_e32 vcc, v0, v14
	s_nop 1
	v_cndmask_b32_e32 v0, v231, v0, vcc
	v_lshlrev_b32_e32 v80, 2, v0
	v_and_b32_e32 v0, 1, v176
	v_cmp_eq_u32_e64 s[36:37], 0, v0
	v_lshlrev_b32_e32 v0, 1, v190
	v_lshl_add_u64 v[14:15], s[0:1], 0, v[0:1]
	v_mul_f32_e32 v0, v64, v86
	s_nop 1
	v_mov_b32_dpp v64, v0 quad_perm:[1,0,3,2] row_mask:0xf bank_mask:0xf
	v_mad_i64_i32 v[84:85], s[0:1], s4, v191, 0
	v_lshl_add_u64 v[84:85], v[84:85], 1, v[14:15]
	s_and_saveexec_b64 s[0:1], s[36:37]
	s_cbranch_execz .LBB0_945
	s_waitcnt lgkmcnt(0)
	v_cvt_pk_bf16_f32 v0, v0, v64
	global_store_dword v[84:85], v0, off
.LBB0_945:
	s_or_b64 exec, exec, s[0:1]
	v_mul_f32_e32 v0, v48, v86
	s_nop 1
	v_mov_b32_dpp v48, v0 quad_perm:[1,0,3,2] row_mask:0xf bank_mask:0xf
	s_and_saveexec_b64 s[0:1], s[36:37]
	s_cbranch_execz .LBB0_947
	s_waitcnt lgkmcnt(0)
	v_cvt_pk_bf16_f32 v0, v0, v48
	global_store_dword v[84:85], v0, off offset:64
.LBB0_947:
	s_or_b64 exec, exec, s[0:1]
	v_mul_f32_e32 v0, v32, v86
	s_nop 1
	v_mov_b32_dpp v32, v0 quad_perm:[1,0,3,2] row_mask:0xf bank_mask:0xf
	s_and_saveexec_b64 s[0:1], s[36:37]
	s_cbranch_execz .LBB0_949
	s_waitcnt lgkmcnt(0)
	v_cvt_pk_bf16_f32 v0, v0, v32
	global_store_dword v[84:85], v0, off offset:128
.LBB0_949:
	s_or_b64 exec, exec, s[0:1]
	v_mul_f32_e32 v0, v16, v86
	s_nop 1
	v_mov_b32_dpp v16, v0 quad_perm:[1,0,3,2] row_mask:0xf bank_mask:0xf
	s_and_saveexec_b64 s[0:1], s[36:37]
	s_cbranch_execz .LBB0_951
	s_waitcnt lgkmcnt(0)
	v_cvt_pk_bf16_f32 v0, v0, v16
	global_store_dword v[84:85], v0, off offset:192
.LBB0_951:
	s_or_b64 exec, exec, s[0:1]
	v_div_scale_f32 v0, s[0:1], v81, v81, 1.0
	s_waitcnt lgkmcnt(0)
	v_rcp_f32_e32 v16, v0
	v_div_scale_f32 v32, vcc, 1.0, v81, 1.0
	v_fma_f32 v48, -v0, v16, 1.0
	v_fmac_f32_e32 v16, v48, v16
	v_mul_f32_e32 v48, v32, v16
	v_fma_f32 v64, -v0, v48, v32
	v_fmac_f32_e32 v48, v64, v16
	v_fma_f32 v0, -v0, v48, v32
	v_div_fmas_f32 v0, v0, v16, v48
	v_div_fixup_f32 v0, v0, v81, 1.0
	v_mul_f32_e32 v16, v65, v0
	s_nop 1
	v_mov_b32_dpp v32, v16 quad_perm:[1,0,3,2] row_mask:0xf bank_mask:0xf
	v_or_b32_e32 v48, 1, v191
	v_mad_i64_i32 v[64:65], s[0:1], s4, v48, 0
	v_lshl_add_u64 v[64:65], v[64:65], 1, v[14:15]
	s_and_saveexec_b64 s[0:1], s[36:37]
	s_cbranch_execz .LBB0_953
	s_waitcnt lgkmcnt(0)
	v_cvt_pk_bf16_f32 v16, v16, v32
	global_store_dword v[64:65], v16, off
.LBB0_953:
	s_or_b64 exec, exec, s[0:1]
	v_mul_f32_e32 v16, v49, v0
	s_waitcnt lgkmcnt(0)
	s_nop 1
	v_mov_b32_dpp v32, v16 quad_perm:[1,0,3,2] row_mask:0xf bank_mask:0xf
	s_and_saveexec_b64 s[0:1], s[36:37]
	s_cbranch_execz .LBB0_955
	s_waitcnt lgkmcnt(0)
	v_cvt_pk_bf16_f32 v16, v16, v32
	global_store_dword v[64:65], v16, off offset:64
.LBB0_955:
	s_or_b64 exec, exec, s[0:1]
	v_mul_f32_e32 v16, v33, v0
	s_waitcnt lgkmcnt(0)
	s_nop 1
	v_mov_b32_dpp v32, v16 quad_perm:[1,0,3,2] row_mask:0xf bank_mask:0xf
	s_and_saveexec_b64 s[0:1], s[36:37]
	s_cbranch_execz .LBB0_957
	s_waitcnt lgkmcnt(0)
	v_cvt_pk_bf16_f32 v16, v16, v32
	global_store_dword v[64:65], v16, off offset:128
.LBB0_957:
	s_or_b64 exec, exec, s[0:1]
	v_mul_f32_e32 v0, v17, v0
	s_nop 1
	v_mov_b32_dpp v16, v0 quad_perm:[1,0,3,2] row_mask:0xf bank_mask:0xf
	s_and_saveexec_b64 s[0:1], s[36:37]
	s_cbranch_execz .LBB0_959
	s_waitcnt lgkmcnt(0)
	v_cvt_pk_bf16_f32 v0, v0, v16
	global_store_dword v[64:65], v0, off offset:192
.LBB0_959:
	s_or_b64 exec, exec, s[0:1]
	v_div_scale_f32 v0, s[0:1], v82, v82, 1.0
	s_waitcnt lgkmcnt(0)
	v_rcp_f32_e32 v16, v0
	v_div_scale_f32 v17, vcc, 1.0, v82, 1.0
	v_fma_f32 v32, -v0, v16, 1.0
	v_fmac_f32_e32 v16, v32, v16
	v_mul_f32_e32 v32, v17, v16
	v_fma_f32 v33, -v0, v32, v17
	v_fmac_f32_e32 v32, v33, v16
	v_fma_f32 v0, -v0, v32, v17
	v_div_fmas_f32 v0, v0, v16, v32
	v_div_fixup_f32 v0, v0, v82, 1.0
	v_mul_f32_e32 v32, v66, v0
	s_nop 1
	v_mov_b32_dpp v33, v32 quad_perm:[1,0,3,2] row_mask:0xf bank_mask:0xf
	v_or_b32_e32 v16, 2, v191
	v_mad_i64_i32 v[16:17], s[0:1], s4, v16, 0
	v_lshl_add_u64 v[16:17], v[16:17], 1, v[14:15]
	s_and_saveexec_b64 s[0:1], s[36:37]
	s_cbranch_execz .LBB0_961
	s_waitcnt lgkmcnt(0)
	v_cvt_pk_bf16_f32 v32, v32, v33
	global_store_dword v[16:17], v32, off
.LBB0_961:
	s_or_b64 exec, exec, s[0:1]
	v_mul_f32_e32 v32, v50, v0
	s_waitcnt lgkmcnt(0)
	s_nop 1
	v_mov_b32_dpp v33, v32 quad_perm:[1,0,3,2] row_mask:0xf bank_mask:0xf
	s_and_saveexec_b64 s[0:1], s[36:37]
	s_cbranch_execz .LBB0_963
	s_waitcnt lgkmcnt(0)
	v_cvt_pk_bf16_f32 v32, v32, v33
	global_store_dword v[16:17], v32, off offset:64
.LBB0_963:
	s_or_b64 exec, exec, s[0:1]
	v_mul_f32_e32 v32, v34, v0
	s_waitcnt lgkmcnt(0)
	s_nop 1
	v_mov_b32_dpp v33, v32 quad_perm:[1,0,3,2] row_mask:0xf bank_mask:0xf
	s_and_saveexec_b64 s[0:1], s[36:37]
	s_cbranch_execz .LBB0_965
	s_waitcnt lgkmcnt(0)
	v_cvt_pk_bf16_f32 v32, v32, v33
	global_store_dword v[16:17], v32, off offset:128
.LBB0_965:
	s_or_b64 exec, exec, s[0:1]
	v_mul_f32_e32 v0, v18, v0
	s_nop 1
	v_mov_b32_dpp v18, v0 quad_perm:[1,0,3,2] row_mask:0xf bank_mask:0xf
	s_and_saveexec_b64 s[0:1], s[36:37]
	s_cbranch_execz .LBB0_967
	s_waitcnt lgkmcnt(0)
	v_cvt_pk_bf16_f32 v0, v0, v18
	global_store_dword v[16:17], v0, off offset:192
.LBB0_967:
	s_or_b64 exec, exec, s[0:1]
	v_div_scale_f32 v0, s[0:1], v83, v83, 1.0
	v_rcp_f32_e32 v16, v0
	v_div_scale_f32 v17, vcc, 1.0, v83, 1.0
	s_waitcnt lgkmcnt(0)
	v_fma_f32 v18, -v0, v16, 1.0
	v_fmac_f32_e32 v16, v18, v16
	v_mul_f32_e32 v18, v17, v16
	v_fma_f32 v32, -v0, v18, v17
	v_fmac_f32_e32 v18, v32, v16
	v_fma_f32 v0, -v0, v18, v17
	v_div_fmas_f32 v0, v0, v16, v18
	v_div_fixup_f32 v0, v0, v83, 1.0
	v_mul_f32_e32 v18, v67, v0
	s_nop 1
	v_mov_b32_dpp v32, v18 quad_perm:[1,0,3,2] row_mask:0xf bank_mask:0xf
	v_or_b32_e32 v16, 3, v191
	v_mad_i64_i32 v[16:17], s[0:1], s4, v16, 0
	v_lshl_add_u64 v[16:17], v[16:17], 1, v[14:15]
	s_and_saveexec_b64 s[0:1], s[36:37]
	s_cbranch_execz .LBB0_969
	s_waitcnt lgkmcnt(0)
	v_cvt_pk_bf16_f32 v18, v18, v32
	global_store_dword v[16:17], v18, off
.LBB0_969:
	s_or_b64 exec, exec, s[0:1]
	v_mul_f32_e32 v18, v51, v0
	s_waitcnt lgkmcnt(0)
	s_nop 1
	v_mov_b32_dpp v32, v18 quad_perm:[1,0,3,2] row_mask:0xf bank_mask:0xf
	s_and_saveexec_b64 s[0:1], s[36:37]
	s_cbranch_execz .LBB0_971
	s_waitcnt lgkmcnt(0)
	v_cvt_pk_bf16_f32 v18, v18, v32
	global_store_dword v[16:17], v18, off offset:64
.LBB0_971:
	s_or_b64 exec, exec, s[0:1]
	v_mul_f32_e32 v18, v35, v0
	s_waitcnt lgkmcnt(0)
	s_nop 1
	v_mov_b32_dpp v32, v18 quad_perm:[1,0,3,2] row_mask:0xf bank_mask:0xf
	s_and_saveexec_b64 s[0:1], s[36:37]
	s_cbranch_execz .LBB0_973
	s_waitcnt lgkmcnt(0)
	v_cvt_pk_bf16_f32 v18, v18, v32
	global_store_dword v[16:17], v18, off offset:128
.LBB0_973:
	s_or_b64 exec, exec, s[0:1]
	v_mul_f32_e32 v0, v19, v0
	s_nop 1
	v_mov_b32_dpp v18, v0 quad_perm:[1,0,3,2] row_mask:0xf bank_mask:0xf
	s_and_saveexec_b64 s[0:1], s[36:37]
	s_cbranch_execz .LBB0_975
	s_waitcnt lgkmcnt(0)
	v_cvt_pk_bf16_f32 v0, v0, v18
	global_store_dword v[16:17], v0, off offset:192
.LBB0_975:
	s_or_b64 exec, exec, s[0:1]
	v_div_scale_f32 v0, s[0:1], v10, v10, 1.0
	v_rcp_f32_e32 v16, v0
	v_div_scale_f32 v17, vcc, 1.0, v10, 1.0
	s_waitcnt lgkmcnt(0)
	v_fma_f32 v18, -v0, v16, 1.0
	v_fmac_f32_e32 v16, v18, v16
	v_mul_f32_e32 v18, v17, v16
	v_fma_f32 v19, -v0, v18, v17
	v_fmac_f32_e32 v18, v19, v16
	v_fma_f32 v0, -v0, v18, v17
	v_div_fmas_f32 v0, v0, v16, v18
	v_div_fixup_f32 v0, v0, v10, 1.0
	v_mul_f32_e32 v10, v68, v0
	s_nop 1
	v_mov_b32_dpp v18, v10 quad_perm:[1,0,3,2] row_mask:0xf bank_mask:0xf
	v_add_u32_e32 v16, 8, v191
	v_mad_i64_i32 v[16:17], s[0:1], s4, v16, 0
	v_lshl_add_u64 v[16:17], v[16:17], 1, v[14:15]
	s_and_saveexec_b64 s[0:1], s[36:37]
	s_cbranch_execz .LBB0_977
	s_waitcnt lgkmcnt(0)
	v_cvt_pk_bf16_f32 v10, v10, v18
	global_store_dword v[16:17], v10, off
.LBB0_977:
	s_or_b64 exec, exec, s[0:1]
	v_mul_f32_e32 v10, v52, v0
	s_waitcnt lgkmcnt(0)
	s_nop 1
	v_mov_b32_dpp v18, v10 quad_perm:[1,0,3,2] row_mask:0xf bank_mask:0xf
	s_and_saveexec_b64 s[0:1], s[36:37]
	s_cbranch_execz .LBB0_979
	s_waitcnt lgkmcnt(0)
	v_cvt_pk_bf16_f32 v10, v10, v18
	global_store_dword v[16:17], v10, off offset:64
.LBB0_979:
	s_or_b64 exec, exec, s[0:1]
	v_mul_f32_e32 v10, v36, v0
	s_waitcnt lgkmcnt(0)
	s_nop 1
	v_mov_b32_dpp v18, v10 quad_perm:[1,0,3,2] row_mask:0xf bank_mask:0xf
	s_and_saveexec_b64 s[0:1], s[36:37]
	s_cbranch_execz .LBB0_981
	s_waitcnt lgkmcnt(0)
	v_cvt_pk_bf16_f32 v10, v10, v18
	global_store_dword v[16:17], v10, off offset:128
.LBB0_981:
	s_or_b64 exec, exec, s[0:1]
	v_mul_f32_e32 v0, v20, v0
	s_nop 1
	v_mov_b32_dpp v10, v0 quad_perm:[1,0,3,2] row_mask:0xf bank_mask:0xf
	s_and_saveexec_b64 s[0:1], s[36:37]
	s_cbranch_execz .LBB0_983
	s_waitcnt lgkmcnt(0)
	v_cvt_pk_bf16_f32 v0, v0, v10
	global_store_dword v[16:17], v0, off offset:192
.LBB0_983:
	s_or_b64 exec, exec, s[0:1]
	v_div_scale_f32 v0, s[0:1], v11, v11, 1.0
	s_waitcnt lgkmcnt(0)
	v_rcp_f32_e32 v10, v0
	v_div_scale_f32 v16, vcc, 1.0, v11, 1.0
	v_fma_f32 v17, -v0, v10, 1.0
	v_fmac_f32_e32 v10, v17, v10
	v_mul_f32_e32 v17, v16, v10
	v_fma_f32 v18, -v0, v17, v16
	v_fmac_f32_e32 v17, v18, v10
	v_fma_f32 v0, -v0, v17, v16
	v_div_fmas_f32 v0, v0, v10, v17
	v_div_fixup_f32 v0, v0, v11, 1.0
	v_mul_f32_e32 v16, v69, v0
	s_nop 1
	v_mov_b32_dpp v17, v16 quad_perm:[1,0,3,2] row_mask:0xf bank_mask:0xf
	v_add_u32_e32 v10, 9, v191
	v_mad_i64_i32 v[10:11], s[0:1], s4, v10, 0
	v_lshl_add_u64 v[10:11], v[10:11], 1, v[14:15]
	s_and_saveexec_b64 s[0:1], s[36:37]
	s_cbranch_execz .LBB0_985
	s_waitcnt lgkmcnt(0)
	v_cvt_pk_bf16_f32 v16, v16, v17
	global_store_dword v[10:11], v16, off
.LBB0_985:
	s_or_b64 exec, exec, s[0:1]
	v_mul_f32_e32 v16, v53, v0
	s_waitcnt lgkmcnt(0)
	s_nop 1
	v_mov_b32_dpp v17, v16 quad_perm:[1,0,3,2] row_mask:0xf bank_mask:0xf
	s_and_saveexec_b64 s[0:1], s[36:37]
	s_cbranch_execz .LBB0_987
	s_waitcnt lgkmcnt(0)
	v_cvt_pk_bf16_f32 v16, v16, v17
	global_store_dword v[10:11], v16, off offset:64
.LBB0_987:
	s_or_b64 exec, exec, s[0:1]
	v_mul_f32_e32 v16, v37, v0
	s_waitcnt lgkmcnt(0)
	s_nop 1
	v_mov_b32_dpp v17, v16 quad_perm:[1,0,3,2] row_mask:0xf bank_mask:0xf
	s_and_saveexec_b64 s[0:1], s[36:37]
	s_cbranch_execz .LBB0_989
	s_waitcnt lgkmcnt(0)
	v_cvt_pk_bf16_f32 v16, v16, v17
	global_store_dword v[10:11], v16, off offset:128
.LBB0_989:
	s_or_b64 exec, exec, s[0:1]
	v_mul_f32_e32 v0, v21, v0
	s_nop 1
	v_mov_b32_dpp v16, v0 quad_perm:[1,0,3,2] row_mask:0xf bank_mask:0xf
	s_and_saveexec_b64 s[0:1], s[36:37]
	s_cbranch_execz .LBB0_991
	s_waitcnt lgkmcnt(0)
	v_cvt_pk_bf16_f32 v0, v0, v16
	global_store_dword v[10:11], v0, off offset:192
.LBB0_991:
	s_or_b64 exec, exec, s[0:1]
	v_div_scale_f32 v0, s[0:1], v12, v12, 1.0
	v_rcp_f32_e32 v10, v0
	v_div_scale_f32 v11, vcc, 1.0, v12, 1.0
	s_waitcnt lgkmcnt(0)
	v_fma_f32 v16, -v0, v10, 1.0
	v_fmac_f32_e32 v10, v16, v10
	v_mul_f32_e32 v16, v11, v10
	v_fma_f32 v17, -v0, v16, v11
	v_fmac_f32_e32 v16, v17, v10
	v_fma_f32 v0, -v0, v16, v11
	v_div_fmas_f32 v0, v0, v10, v16
	v_div_fixup_f32 v0, v0, v12, 1.0
	v_mul_f32_e32 v12, v70, v0
	s_nop 1
	v_mov_b32_dpp v16, v12 quad_perm:[1,0,3,2] row_mask:0xf bank_mask:0xf
	v_add_u32_e32 v10, 10, v191
	v_mad_i64_i32 v[10:11], s[0:1], s4, v10, 0
	v_lshl_add_u64 v[10:11], v[10:11], 1, v[14:15]
	s_and_saveexec_b64 s[0:1], s[36:37]
	s_cbranch_execz .LBB0_993
	s_waitcnt lgkmcnt(0)
	v_cvt_pk_bf16_f32 v12, v12, v16
	global_store_dword v[10:11], v12, off
.LBB0_993:
	s_or_b64 exec, exec, s[0:1]
	v_mul_f32_e32 v12, v54, v0
	s_waitcnt lgkmcnt(0)
	s_nop 1
	v_mov_b32_dpp v16, v12 quad_perm:[1,0,3,2] row_mask:0xf bank_mask:0xf
	s_and_saveexec_b64 s[0:1], s[36:37]
	s_cbranch_execz .LBB0_995
	s_waitcnt lgkmcnt(0)
	v_cvt_pk_bf16_f32 v12, v12, v16
	global_store_dword v[10:11], v12, off offset:64
.LBB0_995:
	s_or_b64 exec, exec, s[0:1]
	v_mul_f32_e32 v12, v38, v0
	s_waitcnt lgkmcnt(0)
	s_nop 1
	v_mov_b32_dpp v16, v12 quad_perm:[1,0,3,2] row_mask:0xf bank_mask:0xf
	s_and_saveexec_b64 s[0:1], s[36:37]
	s_cbranch_execz .LBB0_997
	s_waitcnt lgkmcnt(0)
	v_cvt_pk_bf16_f32 v12, v12, v16
	global_store_dword v[10:11], v12, off offset:128
.LBB0_997:
	s_or_b64 exec, exec, s[0:1]
	v_mul_f32_e32 v0, v22, v0
	s_nop 1
	v_mov_b32_dpp v12, v0 quad_perm:[1,0,3,2] row_mask:0xf bank_mask:0xf
	s_and_saveexec_b64 s[0:1], s[36:37]
	s_cbranch_execz .LBB0_999
	s_waitcnt lgkmcnt(0)
	v_cvt_pk_bf16_f32 v0, v0, v12
	global_store_dword v[10:11], v0, off offset:192
.LBB0_999:
	s_or_b64 exec, exec, s[0:1]
	v_div_scale_f32 v0, s[0:1], v13, v13, 1.0
	v_rcp_f32_e32 v10, v0
	v_div_scale_f32 v11, vcc, 1.0, v13, 1.0
	s_waitcnt lgkmcnt(0)
	v_fma_f32 v12, -v0, v10, 1.0
	v_fmac_f32_e32 v10, v12, v10
	v_mul_f32_e32 v12, v11, v10
	v_fma_f32 v16, -v0, v12, v11
	v_fmac_f32_e32 v12, v16, v10
	v_fma_f32 v0, -v0, v12, v11
	v_div_fmas_f32 v0, v0, v10, v12
	v_div_fixup_f32 v0, v0, v13, 1.0
	v_mul_f32_e32 v12, v71, v0
	s_nop 1
	v_mov_b32_dpp v13, v12 quad_perm:[1,0,3,2] row_mask:0xf bank_mask:0xf
	v_add_u32_e32 v10, 11, v191
	v_mad_i64_i32 v[10:11], s[0:1], s4, v10, 0
	v_lshl_add_u64 v[10:11], v[10:11], 1, v[14:15]
	s_and_saveexec_b64 s[0:1], s[36:37]
	s_cbranch_execz .LBB0_1001
	s_waitcnt lgkmcnt(0)
	v_cvt_pk_bf16_f32 v12, v12, v13
	global_store_dword v[10:11], v12, off
.LBB0_1001:
	s_or_b64 exec, exec, s[0:1]
	v_mul_f32_e32 v12, v55, v0
	s_waitcnt lgkmcnt(0)
	s_nop 1
	v_mov_b32_dpp v13, v12 quad_perm:[1,0,3,2] row_mask:0xf bank_mask:0xf
	s_and_saveexec_b64 s[0:1], s[36:37]
	s_cbranch_execz .LBB0_1003
	s_waitcnt lgkmcnt(0)
	v_cvt_pk_bf16_f32 v12, v12, v13
	global_store_dword v[10:11], v12, off offset:64
.LBB0_1003:
	s_or_b64 exec, exec, s[0:1]
	v_mul_f32_e32 v12, v39, v0
	s_waitcnt lgkmcnt(0)
	s_nop 1
	v_mov_b32_dpp v13, v12 quad_perm:[1,0,3,2] row_mask:0xf bank_mask:0xf
	s_and_saveexec_b64 s[0:1], s[36:37]
	s_cbranch_execz .LBB0_1005
	s_waitcnt lgkmcnt(0)
	v_cvt_pk_bf16_f32 v12, v12, v13
	global_store_dword v[10:11], v12, off offset:128
.LBB0_1005:
	s_or_b64 exec, exec, s[0:1]
	v_mul_f32_e32 v0, v23, v0
	s_nop 1
	v_mov_b32_dpp v12, v0 quad_perm:[1,0,3,2] row_mask:0xf bank_mask:0xf
	s_and_saveexec_b64 s[0:1], s[36:37]
	s_cbranch_execz .LBB0_1007
	s_waitcnt lgkmcnt(0)
	v_cvt_pk_bf16_f32 v0, v0, v12
	global_store_dword v[10:11], v0, off offset:192
.LBB0_1007:
	s_or_b64 exec, exec, s[0:1]
	v_div_scale_f32 v0, s[0:1], v6, v6, 1.0
	v_rcp_f32_e32 v10, v0
	v_div_scale_f32 v11, vcc, 1.0, v6, 1.0
	s_waitcnt lgkmcnt(0)
	v_fma_f32 v12, -v0, v10, 1.0
	v_fmac_f32_e32 v10, v12, v10
	v_mul_f32_e32 v12, v11, v10
	v_fma_f32 v13, -v0, v12, v11
	v_fmac_f32_e32 v12, v13, v10
	v_fma_f32 v0, -v0, v12, v11
	v_div_fmas_f32 v0, v0, v10, v12
	v_div_fixup_f32 v0, v0, v6, 1.0
	v_mul_f32_e32 v6, v72, v0
	s_nop 1
	v_mov_b32_dpp v12, v6 quad_perm:[1,0,3,2] row_mask:0xf bank_mask:0xf
	v_add_u32_e32 v10, 16, v191
	v_mad_i64_i32 v[10:11], s[0:1], s4, v10, 0
	v_lshl_add_u64 v[10:11], v[10:11], 1, v[14:15]
	s_and_saveexec_b64 s[0:1], s[36:37]
	s_cbranch_execz .LBB0_1009
	s_waitcnt lgkmcnt(0)
	v_cvt_pk_bf16_f32 v6, v6, v12
	global_store_dword v[10:11], v6, off
.LBB0_1009:
	s_or_b64 exec, exec, s[0:1]
	v_mul_f32_e32 v6, v56, v0
	s_waitcnt lgkmcnt(0)
	s_nop 1
	v_mov_b32_dpp v12, v6 quad_perm:[1,0,3,2] row_mask:0xf bank_mask:0xf
	s_and_saveexec_b64 s[0:1], s[36:37]
	s_cbranch_execz .LBB0_1011
	s_waitcnt lgkmcnt(0)
	v_cvt_pk_bf16_f32 v6, v6, v12
	global_store_dword v[10:11], v6, off offset:64
.LBB0_1011:
	s_or_b64 exec, exec, s[0:1]
	v_mul_f32_e32 v6, v40, v0
	s_waitcnt lgkmcnt(0)
	s_nop 1
	v_mov_b32_dpp v12, v6 quad_perm:[1,0,3,2] row_mask:0xf bank_mask:0xf
	s_and_saveexec_b64 s[0:1], s[36:37]
	s_cbranch_execz .LBB0_1013
	s_waitcnt lgkmcnt(0)
	v_cvt_pk_bf16_f32 v6, v6, v12
	global_store_dword v[10:11], v6, off offset:128
.LBB0_1013:
	s_or_b64 exec, exec, s[0:1]
	v_mul_f32_e32 v0, v24, v0
	s_nop 1
	v_mov_b32_dpp v6, v0 quad_perm:[1,0,3,2] row_mask:0xf bank_mask:0xf
	s_and_saveexec_b64 s[0:1], s[36:37]
	s_cbranch_execz .LBB0_1015
	s_waitcnt lgkmcnt(0)
	v_cvt_pk_bf16_f32 v0, v0, v6
	global_store_dword v[10:11], v0, off offset:192
.LBB0_1015:
	s_or_b64 exec, exec, s[0:1]
	v_div_scale_f32 v0, s[0:1], v7, v7, 1.0
	s_waitcnt lgkmcnt(0)
	v_rcp_f32_e32 v6, v0
	v_div_scale_f32 v10, vcc, 1.0, v7, 1.0
	v_fma_f32 v11, -v0, v6, 1.0
	v_fmac_f32_e32 v6, v11, v6
	v_mul_f32_e32 v11, v10, v6
	v_fma_f32 v12, -v0, v11, v10
	v_fmac_f32_e32 v11, v12, v6
	v_fma_f32 v0, -v0, v11, v10
	v_div_fmas_f32 v0, v0, v6, v11
	v_div_fixup_f32 v0, v0, v7, 1.0
	v_mul_f32_e32 v10, v73, v0
	s_nop 1
	v_mov_b32_dpp v11, v10 quad_perm:[1,0,3,2] row_mask:0xf bank_mask:0xf
	v_add_u32_e32 v6, 17, v191
	v_mad_i64_i32 v[6:7], s[0:1], s4, v6, 0
	v_lshl_add_u64 v[6:7], v[6:7], 1, v[14:15]
	s_and_saveexec_b64 s[0:1], s[36:37]
	s_cbranch_execz .LBB0_1017
	s_waitcnt lgkmcnt(0)
	v_cvt_pk_bf16_f32 v10, v10, v11
	global_store_dword v[6:7], v10, off
.LBB0_1017:
	s_or_b64 exec, exec, s[0:1]
	v_mul_f32_e32 v10, v57, v0
	s_waitcnt lgkmcnt(0)
	s_nop 1
	v_mov_b32_dpp v11, v10 quad_perm:[1,0,3,2] row_mask:0xf bank_mask:0xf
	s_and_saveexec_b64 s[0:1], s[36:37]
	s_cbranch_execz .LBB0_1019
	s_waitcnt lgkmcnt(0)
	v_cvt_pk_bf16_f32 v10, v10, v11
	global_store_dword v[6:7], v10, off offset:64
.LBB0_1019:
	s_or_b64 exec, exec, s[0:1]
	v_mul_f32_e32 v10, v41, v0
	s_waitcnt lgkmcnt(0)
	s_nop 1
	v_mov_b32_dpp v11, v10 quad_perm:[1,0,3,2] row_mask:0xf bank_mask:0xf
	s_and_saveexec_b64 s[0:1], s[36:37]
	s_cbranch_execz .LBB0_1021
	s_waitcnt lgkmcnt(0)
	v_cvt_pk_bf16_f32 v10, v10, v11
	global_store_dword v[6:7], v10, off offset:128
.LBB0_1021:
	s_or_b64 exec, exec, s[0:1]
	v_mul_f32_e32 v0, v25, v0
	s_nop 1
	v_mov_b32_dpp v10, v0 quad_perm:[1,0,3,2] row_mask:0xf bank_mask:0xf
	s_and_saveexec_b64 s[0:1], s[36:37]
	s_cbranch_execz .LBB0_1023
	s_waitcnt lgkmcnt(0)
	v_cvt_pk_bf16_f32 v0, v0, v10
	global_store_dword v[6:7], v0, off offset:192
.LBB0_1023:
	s_or_b64 exec, exec, s[0:1]
	v_div_scale_f32 v0, s[0:1], v8, v8, 1.0
	v_rcp_f32_e32 v6, v0
	v_div_scale_f32 v7, vcc, 1.0, v8, 1.0
	s_waitcnt lgkmcnt(0)
	v_fma_f32 v10, -v0, v6, 1.0
	v_fmac_f32_e32 v6, v10, v6
	v_mul_f32_e32 v10, v7, v6
	v_fma_f32 v11, -v0, v10, v7
	v_fmac_f32_e32 v10, v11, v6
	v_fma_f32 v0, -v0, v10, v7
	v_div_fmas_f32 v0, v0, v6, v10
	v_div_fixup_f32 v0, v0, v8, 1.0
	v_mul_f32_e32 v8, v74, v0
	s_nop 1
	v_mov_b32_dpp v10, v8 quad_perm:[1,0,3,2] row_mask:0xf bank_mask:0xf
	v_add_u32_e32 v6, 18, v191
	v_mad_i64_i32 v[6:7], s[0:1], s4, v6, 0
	v_lshl_add_u64 v[6:7], v[6:7], 1, v[14:15]
	s_and_saveexec_b64 s[0:1], s[36:37]
	s_cbranch_execz .LBB0_1025
	s_waitcnt lgkmcnt(0)
	v_cvt_pk_bf16_f32 v8, v8, v10
	global_store_dword v[6:7], v8, off
.LBB0_1025:
	s_or_b64 exec, exec, s[0:1]
	v_mul_f32_e32 v8, v58, v0
	s_waitcnt lgkmcnt(0)
	s_nop 1
	v_mov_b32_dpp v10, v8 quad_perm:[1,0,3,2] row_mask:0xf bank_mask:0xf
	s_and_saveexec_b64 s[0:1], s[36:37]
	s_cbranch_execz .LBB0_1027
	s_waitcnt lgkmcnt(0)
	v_cvt_pk_bf16_f32 v8, v8, v10
	global_store_dword v[6:7], v8, off offset:64
.LBB0_1027:
	s_or_b64 exec, exec, s[0:1]
	v_mul_f32_e32 v8, v42, v0
	s_waitcnt lgkmcnt(0)
	s_nop 1
	v_mov_b32_dpp v10, v8 quad_perm:[1,0,3,2] row_mask:0xf bank_mask:0xf
	s_and_saveexec_b64 s[0:1], s[36:37]
	s_cbranch_execz .LBB0_1029
	s_waitcnt lgkmcnt(0)
	v_cvt_pk_bf16_f32 v8, v8, v10
	global_store_dword v[6:7], v8, off offset:128
.LBB0_1029:
	s_or_b64 exec, exec, s[0:1]
	v_mul_f32_e32 v0, v26, v0
	s_nop 1
	v_mov_b32_dpp v8, v0 quad_perm:[1,0,3,2] row_mask:0xf bank_mask:0xf
	s_and_saveexec_b64 s[0:1], s[36:37]
	s_cbranch_execz .LBB0_1031
	s_waitcnt lgkmcnt(0)
	v_cvt_pk_bf16_f32 v0, v0, v8
	global_store_dword v[6:7], v0, off offset:192
.LBB0_1031:
	s_or_b64 exec, exec, s[0:1]
	v_div_scale_f32 v0, s[0:1], v9, v9, 1.0
	v_rcp_f32_e32 v6, v0
	v_div_scale_f32 v7, vcc, 1.0, v9, 1.0
	s_waitcnt lgkmcnt(0)
	v_fma_f32 v8, -v0, v6, 1.0
	v_fmac_f32_e32 v6, v8, v6
	v_mul_f32_e32 v8, v7, v6
	v_fma_f32 v10, -v0, v8, v7
	v_fmac_f32_e32 v8, v10, v6
	v_fma_f32 v0, -v0, v8, v7
	v_div_fmas_f32 v0, v0, v6, v8
	v_div_fixup_f32 v0, v0, v9, 1.0
	v_mul_f32_e32 v8, v75, v0
	s_nop 1
	v_mov_b32_dpp v9, v8 quad_perm:[1,0,3,2] row_mask:0xf bank_mask:0xf
	v_add_u32_e32 v6, 19, v191
	v_mad_i64_i32 v[6:7], s[0:1], s4, v6, 0
	v_lshl_add_u64 v[6:7], v[6:7], 1, v[14:15]
	s_and_saveexec_b64 s[0:1], s[36:37]
	s_cbranch_execz .LBB0_1033
	s_waitcnt lgkmcnt(0)
	v_cvt_pk_bf16_f32 v8, v8, v9
	global_store_dword v[6:7], v8, off
.LBB0_1033:
	s_or_b64 exec, exec, s[0:1]
	v_mul_f32_e32 v8, v59, v0
	s_waitcnt lgkmcnt(0)
	s_nop 1
	v_mov_b32_dpp v9, v8 quad_perm:[1,0,3,2] row_mask:0xf bank_mask:0xf
	s_and_saveexec_b64 s[0:1], s[36:37]
	s_cbranch_execz .LBB0_1035
	s_waitcnt lgkmcnt(0)
	v_cvt_pk_bf16_f32 v8, v8, v9
	global_store_dword v[6:7], v8, off offset:64
.LBB0_1035:
	s_or_b64 exec, exec, s[0:1]
	v_mul_f32_e32 v8, v43, v0
	s_waitcnt lgkmcnt(0)
	s_nop 1
	v_mov_b32_dpp v9, v8 quad_perm:[1,0,3,2] row_mask:0xf bank_mask:0xf
	s_and_saveexec_b64 s[0:1], s[36:37]
	s_cbranch_execz .LBB0_1037
	s_waitcnt lgkmcnt(0)
	v_cvt_pk_bf16_f32 v8, v8, v9
	global_store_dword v[6:7], v8, off offset:128
.LBB0_1037:
	s_or_b64 exec, exec, s[0:1]
	v_mul_f32_e32 v0, v27, v0
	s_nop 1
	v_mov_b32_dpp v8, v0 quad_perm:[1,0,3,2] row_mask:0xf bank_mask:0xf
	s_and_saveexec_b64 s[0:1], s[36:37]
	s_cbranch_execz .LBB0_1039
	s_waitcnt lgkmcnt(0)
	v_cvt_pk_bf16_f32 v0, v0, v8
	global_store_dword v[6:7], v0, off offset:192
.LBB0_1039:
	s_or_b64 exec, exec, s[0:1]
	v_div_scale_f32 v0, s[0:1], v2, v2, 1.0
	v_rcp_f32_e32 v6, v0
	v_div_scale_f32 v7, vcc, 1.0, v2, 1.0
	s_waitcnt lgkmcnt(0)
	v_fma_f32 v8, -v0, v6, 1.0
	v_fmac_f32_e32 v6, v8, v6
	v_mul_f32_e32 v8, v7, v6
	v_fma_f32 v9, -v0, v8, v7
	v_fmac_f32_e32 v8, v9, v6
	v_fma_f32 v0, -v0, v8, v7
	v_div_fmas_f32 v0, v0, v6, v8
	v_div_fixup_f32 v0, v0, v2, 1.0
	v_mul_f32_e32 v2, v76, v0
	s_nop 1
	v_mov_b32_dpp v8, v2 quad_perm:[1,0,3,2] row_mask:0xf bank_mask:0xf
	v_add_u32_e32 v6, 24, v191
	v_mad_i64_i32 v[6:7], s[0:1], s4, v6, 0
	v_lshl_add_u64 v[6:7], v[6:7], 1, v[14:15]
	s_and_saveexec_b64 s[0:1], s[36:37]
	s_cbranch_execz .LBB0_1041
	s_waitcnt lgkmcnt(0)
	v_cvt_pk_bf16_f32 v2, v2, v8
	global_store_dword v[6:7], v2, off
.LBB0_1041:
	s_or_b64 exec, exec, s[0:1]
	v_mul_f32_e32 v2, v60, v0
	s_waitcnt lgkmcnt(0)
	s_nop 1
	v_mov_b32_dpp v8, v2 quad_perm:[1,0,3,2] row_mask:0xf bank_mask:0xf
	s_and_saveexec_b64 s[0:1], s[36:37]
	s_cbranch_execz .LBB0_1043
	s_waitcnt lgkmcnt(0)
	v_cvt_pk_bf16_f32 v2, v2, v8
	global_store_dword v[6:7], v2, off offset:64
.LBB0_1043:
	s_or_b64 exec, exec, s[0:1]
	v_mul_f32_e32 v2, v44, v0
	s_waitcnt lgkmcnt(0)
	s_nop 1
	v_mov_b32_dpp v8, v2 quad_perm:[1,0,3,2] row_mask:0xf bank_mask:0xf
	s_and_saveexec_b64 s[0:1], s[36:37]
	s_cbranch_execz .LBB0_1045
	s_waitcnt lgkmcnt(0)
	v_cvt_pk_bf16_f32 v2, v2, v8
	global_store_dword v[6:7], v2, off offset:128
.LBB0_1045:
	s_or_b64 exec, exec, s[0:1]
	v_mul_f32_e32 v0, v28, v0
	s_nop 1
	v_mov_b32_dpp v2, v0 quad_perm:[1,0,3,2] row_mask:0xf bank_mask:0xf
	s_and_saveexec_b64 s[0:1], s[36:37]
	s_cbranch_execz .LBB0_1047
	s_waitcnt lgkmcnt(0)
	v_cvt_pk_bf16_f32 v0, v0, v2
	global_store_dword v[6:7], v0, off offset:192
.LBB0_1047:
	s_or_b64 exec, exec, s[0:1]
	v_div_scale_f32 v0, s[0:1], v3, v3, 1.0
	s_waitcnt lgkmcnt(0)
	v_rcp_f32_e32 v2, v0
	v_div_scale_f32 v6, vcc, 1.0, v3, 1.0
	v_fma_f32 v7, -v0, v2, 1.0
	v_fmac_f32_e32 v2, v7, v2
	v_mul_f32_e32 v7, v6, v2
	v_fma_f32 v8, -v0, v7, v6
	v_fmac_f32_e32 v7, v8, v2
	v_fma_f32 v0, -v0, v7, v6
	v_div_fmas_f32 v0, v0, v2, v7
	v_div_fixup_f32 v0, v0, v3, 1.0
	v_mul_f32_e32 v6, v77, v0
	s_nop 1
	v_mov_b32_dpp v7, v6 quad_perm:[1,0,3,2] row_mask:0xf bank_mask:0xf
	v_add_u32_e32 v2, 25, v191
	v_mad_i64_i32 v[2:3], s[0:1], s4, v2, 0
	v_lshl_add_u64 v[2:3], v[2:3], 1, v[14:15]
	s_and_saveexec_b64 s[0:1], s[36:37]
	s_cbranch_execz .LBB0_1049
	s_waitcnt lgkmcnt(0)
	v_cvt_pk_bf16_f32 v6, v6, v7
	global_store_dword v[2:3], v6, off
.LBB0_1049:
	s_or_b64 exec, exec, s[0:1]
	v_mul_f32_e32 v6, v61, v0
	s_waitcnt lgkmcnt(0)
	s_nop 1
	v_mov_b32_dpp v7, v6 quad_perm:[1,0,3,2] row_mask:0xf bank_mask:0xf
	s_and_saveexec_b64 s[0:1], s[36:37]
	s_cbranch_execz .LBB0_1051
	s_waitcnt lgkmcnt(0)
	v_cvt_pk_bf16_f32 v6, v6, v7
	global_store_dword v[2:3], v6, off offset:64
.LBB0_1051:
	s_or_b64 exec, exec, s[0:1]
	v_mul_f32_e32 v6, v45, v0
	s_waitcnt lgkmcnt(0)
	s_nop 1
	v_mov_b32_dpp v7, v6 quad_perm:[1,0,3,2] row_mask:0xf bank_mask:0xf
	s_and_saveexec_b64 s[0:1], s[36:37]
	s_cbranch_execz .LBB0_1053
	s_waitcnt lgkmcnt(0)
	v_cvt_pk_bf16_f32 v6, v6, v7
	global_store_dword v[2:3], v6, off offset:128
.LBB0_1053:
	s_or_b64 exec, exec, s[0:1]
	v_mul_f32_e32 v0, v29, v0
	s_nop 1
	v_mov_b32_dpp v6, v0 quad_perm:[1,0,3,2] row_mask:0xf bank_mask:0xf
	s_and_saveexec_b64 s[0:1], s[36:37]
	s_cbranch_execz .LBB0_1055
	s_waitcnt lgkmcnt(0)
	v_cvt_pk_bf16_f32 v0, v0, v6
	global_store_dword v[2:3], v0, off offset:192
.LBB0_1055:
	s_or_b64 exec, exec, s[0:1]
	v_div_scale_f32 v0, s[0:1], v4, v4, 1.0
	v_rcp_f32_e32 v2, v0
	v_div_scale_f32 v3, vcc, 1.0, v4, 1.0
	s_waitcnt lgkmcnt(0)
	v_fma_f32 v6, -v0, v2, 1.0
	v_fmac_f32_e32 v2, v6, v2
	v_mul_f32_e32 v6, v3, v2
	v_fma_f32 v7, -v0, v6, v3
	v_fmac_f32_e32 v6, v7, v2
	v_fma_f32 v0, -v0, v6, v3
	v_div_fmas_f32 v0, v0, v2, v6
	v_div_fixup_f32 v0, v0, v4, 1.0
	v_mul_f32_e32 v4, v78, v0
	s_nop 1
	v_mov_b32_dpp v6, v4 quad_perm:[1,0,3,2] row_mask:0xf bank_mask:0xf
	v_add_u32_e32 v2, 26, v191
	v_mad_i64_i32 v[2:3], s[0:1], s4, v2, 0
	v_lshl_add_u64 v[2:3], v[2:3], 1, v[14:15]
	s_and_saveexec_b64 s[0:1], s[36:37]
	s_cbranch_execz .LBB0_1057
	s_waitcnt lgkmcnt(0)
	v_cvt_pk_bf16_f32 v4, v4, v6
	global_store_dword v[2:3], v4, off
.LBB0_1057:
	s_or_b64 exec, exec, s[0:1]
	v_mul_f32_e32 v4, v62, v0
	s_waitcnt lgkmcnt(0)
	s_nop 1
	v_mov_b32_dpp v6, v4 quad_perm:[1,0,3,2] row_mask:0xf bank_mask:0xf
	s_and_saveexec_b64 s[0:1], s[36:37]
	s_cbranch_execz .LBB0_1059
	s_waitcnt lgkmcnt(0)
	v_cvt_pk_bf16_f32 v4, v4, v6
	global_store_dword v[2:3], v4, off offset:64
.LBB0_1059:
	s_or_b64 exec, exec, s[0:1]
	v_mul_f32_e32 v4, v46, v0
	s_waitcnt lgkmcnt(0)
	s_nop 1
	v_mov_b32_dpp v6, v4 quad_perm:[1,0,3,2] row_mask:0xf bank_mask:0xf
	s_and_saveexec_b64 s[0:1], s[36:37]
	s_cbranch_execz .LBB0_1061
	s_waitcnt lgkmcnt(0)
	v_cvt_pk_bf16_f32 v4, v4, v6
	global_store_dword v[2:3], v4, off offset:128
.LBB0_1061:
	s_or_b64 exec, exec, s[0:1]
	v_mul_f32_e32 v0, v30, v0
	s_nop 1
	v_mov_b32_dpp v4, v0 quad_perm:[1,0,3,2] row_mask:0xf bank_mask:0xf
	s_and_saveexec_b64 s[0:1], s[36:37]
	s_cbranch_execz .LBB0_1063
	s_waitcnt lgkmcnt(0)
	v_cvt_pk_bf16_f32 v0, v0, v4
	global_store_dword v[2:3], v0, off offset:192
.LBB0_1063:
	s_or_b64 exec, exec, s[0:1]
	v_div_scale_f32 v0, s[0:1], v5, v5, 1.0
	v_rcp_f32_e32 v2, v0
	v_div_scale_f32 v3, vcc, 1.0, v5, 1.0
	s_waitcnt lgkmcnt(0)
	v_fma_f32 v4, -v0, v2, 1.0
	v_fmac_f32_e32 v2, v4, v2
	v_mul_f32_e32 v4, v3, v2
	v_fma_f32 v6, -v0, v4, v3
	v_fmac_f32_e32 v4, v6, v2
	v_fma_f32 v0, -v0, v4, v3
	v_div_fmas_f32 v0, v0, v2, v4
	v_div_fixup_f32 v0, v0, v5, 1.0
	v_mul_f32_e32 v4, v79, v0
	s_nop 1
	v_mov_b32_dpp v5, v4 quad_perm:[1,0,3,2] row_mask:0xf bank_mask:0xf
	v_add_u32_e32 v2, 27, v191
	v_mad_i64_i32 v[2:3], s[0:1], s4, v2, 0
	v_lshl_add_u64 v[2:3], v[2:3], 1, v[14:15]
	s_and_saveexec_b64 s[0:1], s[36:37]
	s_cbranch_execz .LBB0_1065
	s_waitcnt lgkmcnt(0)
	v_cvt_pk_bf16_f32 v4, v4, v5
	global_store_dword v[2:3], v4, off
.LBB0_1065:
	s_or_b64 exec, exec, s[0:1]
	v_mul_f32_e32 v4, v63, v0
	s_waitcnt lgkmcnt(0)
	s_nop 1
	v_mov_b32_dpp v5, v4 quad_perm:[1,0,3,2] row_mask:0xf bank_mask:0xf
	s_and_saveexec_b64 s[0:1], s[36:37]
	s_cbranch_execz .LBB0_1067
	s_waitcnt lgkmcnt(0)
	v_cvt_pk_bf16_f32 v4, v4, v5
	global_store_dword v[2:3], v4, off offset:64
.LBB0_1067:
	s_or_b64 exec, exec, s[0:1]
	v_mul_f32_e32 v4, v47, v0
	s_waitcnt lgkmcnt(0)
	s_nop 1
	v_mov_b32_dpp v5, v4 quad_perm:[1,0,3,2] row_mask:0xf bank_mask:0xf
	s_and_saveexec_b64 s[0:1], s[36:37]
	s_cbranch_execz .LBB0_1069
	s_waitcnt lgkmcnt(0)
	v_cvt_pk_bf16_f32 v4, v4, v5
	global_store_dword v[2:3], v4, off offset:128
.LBB0_1069:
	s_or_b64 exec, exec, s[0:1]
	v_mul_f32_e32 v0, v31, v0
	s_nop 1
	v_mov_b32_dpp v4, v0 quad_perm:[1,0,3,2] row_mask:0xf bank_mask:0xf
	s_and_saveexec_b64 s[0:1], s[36:37]
	s_xor_b64 s[0:1], exec, s[0:1]
	s_cbranch_execz .LBB0_1071
	s_waitcnt lgkmcnt(0)
	v_cvt_pk_bf16_f32 v0, v0, v4
	global_store_dword v[2:3], v0, off offset:192

.LBB0_1118:
	s_waitcnt vmcnt(0)
	v_readlane_b32 s0, v255, 37
	v_readlane_b32 s1, v255, 38
	s_and_b64 vcc, exec, s[0:1]
	s_barrier
	s_cbranch_vccnz .LBB0_1248
	v_readlane_b32 s0, v255, 24
	v_and_b32_e32 v2, 64, v231
	v_readlane_b32 s1, v255, 25
	s_add_i32 s0, s0, s55
	v_xor_b32_e32 v0, 1, v231
	v_add_u32_e32 v2, 64, v2
	s_mul_hi_i32 s1, s0, 0xc00
	s_mulk_i32 s0, 0xc00
	v_readlane_b32 s4, v250, 63
	v_cmp_lt_i32_e32 vcc, v0, v2
	v_readlane_b32 s5, v251, 0
	s_add_u32 s0, s4, s0
	v_readlane_b32 s2, v255, 36
	v_cndmask_b32_e32 v0, v231, v0, vcc
	s_addc_u32 s1, s5, s1
	s_lshl_b32 s2, s2, 1
	v_lshlrev_b32_e32 v6, 2, v0
	s_add_u32 s0, s0, s2
	v_and_b32_e32 v0, 1, v154
	s_nop 1
	v_mov_b32_dpp v8, v16 quad_perm:[1,0,3,2] row_mask:0xf bank_mask:0xf
	s_addc_u32 s1, s1, 0
	v_cmp_eq_u32_e32 vcc, 0, v0
	v_lshlrev_b32_e32 v0, 1, v155
	v_lshl_add_u64 v[2:3], s[0:1], 0, v[0:1]
	s_mov_b64 s[0:1], 0x2c500400
	v_lshlrev_b32_e32 v7, 2, v156
	v_lshl_add_u64 v[2:3], v[2:3], 0, s[0:1]
	s_movk_i32 s0, 0xc00
	v_mad_i64_i32 v[4:5], s[0:1], v7, s0, v[2:3]
	v_readlane_b32 s6, v251, 1
	v_readlane_b32 s7, v251, 2
	s_and_saveexec_b64 s[0:1], vcc
	s_cbranch_execz .LBB0_1121
	s_waitcnt lgkmcnt(0)
	v_cvt_pk_bf16_f32 v0, v16, v8
	global_store_dword v[4:5], v0, off
.LBB0_1121:
	s_or_b64 exec, exec, s[0:1]
	s_nop 1
	v_mov_b32_dpp v0, v32 quad_perm:[1,0,3,2] row_mask:0xf bank_mask:0xf
	s_and_saveexec_b64 s[0:1], vcc
	s_cbranch_execz .LBB0_1123
	s_waitcnt lgkmcnt(0)
	v_cvt_pk_bf16_f32 v0, v32, v0
	global_store_dword v[4:5], v0, off offset:64
.LBB0_1123:
	s_or_b64 exec, exec, s[0:1]
	s_waitcnt lgkmcnt(0)
	s_nop 1
	v_mov_b32_dpp v0, v48 quad_perm:[1,0,3,2] row_mask:0xf bank_mask:0xf
	s_and_saveexec_b64 s[0:1], vcc
	s_cbranch_execz .LBB0_1125
	s_waitcnt lgkmcnt(0)
	v_cvt_pk_bf16_f32 v0, v48, v0
	global_store_dword v[4:5], v0, off offset:128
.LBB0_1125:
	s_or_b64 exec, exec, s[0:1]
	s_waitcnt lgkmcnt(0)
	s_nop 1
	v_mov_b32_dpp v0, v64 quad_perm:[1,0,3,2] row_mask:0xf bank_mask:0xf
	s_and_saveexec_b64 s[0:1], vcc
	s_cbranch_execz .LBB0_1127
	s_waitcnt lgkmcnt(0)
	v_cvt_pk_bf16_f32 v0, v64, v0
	global_store_dword v[4:5], v0, off offset:192
.LBB0_1127:
	s_or_b64 exec, exec, s[0:1]
	s_waitcnt lgkmcnt(0)
	v_or_b32_e32 v0, 1, v7
	s_movk_i32 s0, 0xc00
	v_mad_i64_i32 v[4:5], s[0:1], v0, s0, v[2:3]
	s_nop 1
	v_mov_b32_dpp v0, v17 quad_perm:[1,0,3,2] row_mask:0xf bank_mask:0xf
	s_and_saveexec_b64 s[0:1], vcc
	s_cbranch_execz .LBB0_1129
	s_waitcnt lgkmcnt(0)
	v_cvt_pk_bf16_f32 v0, v17, v0
	global_store_dword v[4:5], v0, off
.LBB0_1129:
	s_or_b64 exec, exec, s[0:1]
	s_waitcnt lgkmcnt(0)
	s_nop 1
	v_mov_b32_dpp v0, v33 quad_perm:[1,0,3,2] row_mask:0xf bank_mask:0xf
	s_and_saveexec_b64 s[0:1], vcc
	s_cbranch_execz .LBB0_1131
	s_waitcnt lgkmcnt(0)
	v_cvt_pk_bf16_f32 v0, v33, v0
	global_store_dword v[4:5], v0, off offset:64
.LBB0_1131:
	s_or_b64 exec, exec, s[0:1]
	s_waitcnt lgkmcnt(0)
	s_nop 1
	v_mov_b32_dpp v0, v49 quad_perm:[1,0,3,2] row_mask:0xf bank_mask:0xf
	s_and_saveexec_b64 s[0:1], vcc
	s_cbranch_execz .LBB0_1133
	s_waitcnt lgkmcnt(0)
	v_cvt_pk_bf16_f32 v0, v49, v0
	global_store_dword v[4:5], v0, off offset:128
.LBB0_1133:
	s_or_b64 exec, exec, s[0:1]
	s_waitcnt lgkmcnt(0)
	s_nop 1
	v_mov_b32_dpp v0, v65 quad_perm:[1,0,3,2] row_mask:0xf bank_mask:0xf
	s_and_saveexec_b64 s[0:1], vcc
	s_cbranch_execz .LBB0_1135
	s_waitcnt lgkmcnt(0)
	v_cvt_pk_bf16_f32 v0, v65, v0
	global_store_dword v[4:5], v0, off offset:192
.LBB0_1135:
	s_or_b64 exec, exec, s[0:1]
	s_waitcnt lgkmcnt(0)
	v_or_b32_e32 v0, 2, v7
	s_movk_i32 s0, 0xc00
	v_mad_i64_i32 v[4:5], s[0:1], v0, s0, v[2:3]
	s_nop 1
	v_mov_b32_dpp v0, v18 quad_perm:[1,0,3,2] row_mask:0xf bank_mask:0xf
	s_and_saveexec_b64 s[0:1], vcc
	s_cbranch_execz .LBB0_1137
	s_waitcnt lgkmcnt(0)
	v_cvt_pk_bf16_f32 v0, v18, v0
	global_store_dword v[4:5], v0, off
.LBB0_1137:
	s_or_b64 exec, exec, s[0:1]
	s_waitcnt lgkmcnt(0)
	s_nop 1
	v_mov_b32_dpp v0, v34 quad_perm:[1,0,3,2] row_mask:0xf bank_mask:0xf
	s_and_saveexec_b64 s[0:1], vcc
	s_cbranch_execz .LBB0_1139
	s_waitcnt lgkmcnt(0)
	v_cvt_pk_bf16_f32 v0, v34, v0
	global_store_dword v[4:5], v0, off offset:64
.LBB0_1139:
	s_or_b64 exec, exec, s[0:1]
	s_waitcnt lgkmcnt(0)
	s_nop 1
	v_mov_b32_dpp v0, v50 quad_perm:[1,0,3,2] row_mask:0xf bank_mask:0xf
	s_and_saveexec_b64 s[0:1], vcc
	s_cbranch_execz .LBB0_1141
	s_waitcnt lgkmcnt(0)
	v_cvt_pk_bf16_f32 v0, v50, v0
	global_store_dword v[4:5], v0, off offset:128
.LBB0_1141:
	s_or_b64 exec, exec, s[0:1]
	s_waitcnt lgkmcnt(0)
	s_nop 1
	v_mov_b32_dpp v0, v66 quad_perm:[1,0,3,2] row_mask:0xf bank_mask:0xf
	s_and_saveexec_b64 s[0:1], vcc
	s_cbranch_execz .LBB0_1143
	s_waitcnt lgkmcnt(0)
	v_cvt_pk_bf16_f32 v0, v66, v0
	global_store_dword v[4:5], v0, off offset:192
.LBB0_1143:
	s_or_b64 exec, exec, s[0:1]
	s_waitcnt lgkmcnt(0)
	v_or_b32_e32 v0, 3, v7
	s_movk_i32 s0, 0xc00
	v_mad_i64_i32 v[4:5], s[0:1], v0, s0, v[2:3]
	s_nop 1
	v_mov_b32_dpp v0, v19 quad_perm:[1,0,3,2] row_mask:0xf bank_mask:0xf
	s_and_saveexec_b64 s[0:1], vcc
	s_cbranch_execz .LBB0_1145
	s_waitcnt lgkmcnt(0)
	v_cvt_pk_bf16_f32 v0, v19, v0
	global_store_dword v[4:5], v0, off
.LBB0_1145:
	s_or_b64 exec, exec, s[0:1]
	s_waitcnt lgkmcnt(0)
	s_nop 1
	v_mov_b32_dpp v0, v35 quad_perm:[1,0,3,2] row_mask:0xf bank_mask:0xf
	s_and_saveexec_b64 s[0:1], vcc
	s_cbranch_execz .LBB0_1147
	s_waitcnt lgkmcnt(0)
	v_cvt_pk_bf16_f32 v0, v35, v0
	global_store_dword v[4:5], v0, off offset:64
.LBB0_1147:
	s_or_b64 exec, exec, s[0:1]
	s_waitcnt lgkmcnt(0)
	s_nop 1
	v_mov_b32_dpp v0, v51 quad_perm:[1,0,3,2] row_mask:0xf bank_mask:0xf
	s_and_saveexec_b64 s[0:1], vcc
	s_cbranch_execz .LBB0_1149
	s_waitcnt lgkmcnt(0)
	v_cvt_pk_bf16_f32 v0, v51, v0
	global_store_dword v[4:5], v0, off offset:128
.LBB0_1149:
	s_or_b64 exec, exec, s[0:1]
	s_waitcnt lgkmcnt(0)
	s_nop 1
	v_mov_b32_dpp v0, v67 quad_perm:[1,0,3,2] row_mask:0xf bank_mask:0xf
	s_and_saveexec_b64 s[0:1], vcc
	s_cbranch_execz .LBB0_1151
	s_waitcnt lgkmcnt(0)
	v_cvt_pk_bf16_f32 v0, v67, v0
	global_store_dword v[4:5], v0, off offset:192
.LBB0_1151:
	s_or_b64 exec, exec, s[0:1]
	s_waitcnt lgkmcnt(0)
	v_add_u32_e32 v0, 8, v7
	s_movk_i32 s0, 0xc00
	v_mad_i64_i32 v[4:5], s[0:1], v0, s0, v[2:3]
	s_nop 1
	v_mov_b32_dpp v0, v20 quad_perm:[1,0,3,2] row_mask:0xf bank_mask:0xf
	s_and_saveexec_b64 s[0:1], vcc
	s_cbranch_execz .LBB0_1153
	s_waitcnt lgkmcnt(0)
	v_cvt_pk_bf16_f32 v0, v20, v0
	global_store_dword v[4:5], v0, off
.LBB0_1153:
	s_or_b64 exec, exec, s[0:1]
	s_waitcnt lgkmcnt(0)
	s_nop 1
	v_mov_b32_dpp v0, v36 quad_perm:[1,0,3,2] row_mask:0xf bank_mask:0xf
	s_and_saveexec_b64 s[0:1], vcc
	s_cbranch_execz .LBB0_1155
	s_waitcnt lgkmcnt(0)
	v_cvt_pk_bf16_f32 v0, v36, v0
	global_store_dword v[4:5], v0, off offset:64
.LBB0_1155:
	s_or_b64 exec, exec, s[0:1]
	s_waitcnt lgkmcnt(0)
	s_nop 1
	v_mov_b32_dpp v0, v52 quad_perm:[1,0,3,2] row_mask:0xf bank_mask:0xf
	s_and_saveexec_b64 s[0:1], vcc
	s_cbranch_execz .LBB0_1157
	s_waitcnt lgkmcnt(0)
	v_cvt_pk_bf16_f32 v0, v52, v0
	global_store_dword v[4:5], v0, off offset:128
.LBB0_1157:
	s_or_b64 exec, exec, s[0:1]
	s_waitcnt lgkmcnt(0)
	s_nop 1
	v_mov_b32_dpp v0, v68 quad_perm:[1,0,3,2] row_mask:0xf bank_mask:0xf
	s_and_saveexec_b64 s[0:1], vcc
	s_cbranch_execz .LBB0_1159
	s_waitcnt lgkmcnt(0)
	v_cvt_pk_bf16_f32 v0, v68, v0
	global_store_dword v[4:5], v0, off offset:192
.LBB0_1159:
	s_or_b64 exec, exec, s[0:1]
	s_waitcnt lgkmcnt(0)
	v_add_u32_e32 v0, 9, v7
	s_movk_i32 s0, 0xc00
	v_mad_i64_i32 v[4:5], s[0:1], v0, s0, v[2:3]
	s_nop 1
	v_mov_b32_dpp v0, v21 quad_perm:[1,0,3,2] row_mask:0xf bank_mask:0xf
	s_and_saveexec_b64 s[0:1], vcc
	s_cbranch_execz .LBB0_1161
	s_waitcnt lgkmcnt(0)
	v_cvt_pk_bf16_f32 v0, v21, v0
	global_store_dword v[4:5], v0, off
.LBB0_1161:
	s_or_b64 exec, exec, s[0:1]
	s_waitcnt lgkmcnt(0)
	s_nop 1
	v_mov_b32_dpp v0, v37 quad_perm:[1,0,3,2] row_mask:0xf bank_mask:0xf
	s_and_saveexec_b64 s[0:1], vcc
	s_cbranch_execz .LBB0_1163
	s_waitcnt lgkmcnt(0)
	v_cvt_pk_bf16_f32 v0, v37, v0
	global_store_dword v[4:5], v0, off offset:64
.LBB0_1163:
	s_or_b64 exec, exec, s[0:1]
	s_waitcnt lgkmcnt(0)
	s_nop 1
	v_mov_b32_dpp v0, v53 quad_perm:[1,0,3,2] row_mask:0xf bank_mask:0xf
	s_and_saveexec_b64 s[0:1], vcc
	s_cbranch_execz .LBB0_1165
	s_waitcnt lgkmcnt(0)
	v_cvt_pk_bf16_f32 v0, v53, v0
	global_store_dword v[4:5], v0, off offset:128
.LBB0_1165:
	s_or_b64 exec, exec, s[0:1]
	s_waitcnt lgkmcnt(0)
	s_nop 1
	v_mov_b32_dpp v0, v69 quad_perm:[1,0,3,2] row_mask:0xf bank_mask:0xf
	s_and_saveexec_b64 s[0:1], vcc
	s_cbranch_execz .LBB0_1167
	s_waitcnt lgkmcnt(0)
	v_cvt_pk_bf16_f32 v0, v69, v0
	global_store_dword v[4:5], v0, off offset:192
.LBB0_1167:
	s_or_b64 exec, exec, s[0:1]
	s_waitcnt lgkmcnt(0)
	v_add_u32_e32 v0, 10, v7
	s_movk_i32 s0, 0xc00
	v_mad_i64_i32 v[4:5], s[0:1], v0, s0, v[2:3]
	s_nop 1
	v_mov_b32_dpp v0, v22 quad_perm:[1,0,3,2] row_mask:0xf bank_mask:0xf
	s_and_saveexec_b64 s[0:1], vcc
	s_cbranch_execz .LBB0_1169
	s_waitcnt lgkmcnt(0)
	v_cvt_pk_bf16_f32 v0, v22, v0
	global_store_dword v[4:5], v0, off
.LBB0_1169:
	s_or_b64 exec, exec, s[0:1]
	s_waitcnt lgkmcnt(0)
	s_nop 1
	v_mov_b32_dpp v0, v38 quad_perm:[1,0,3,2] row_mask:0xf bank_mask:0xf
	s_and_saveexec_b64 s[0:1], vcc
	s_cbranch_execz .LBB0_1171
	s_waitcnt lgkmcnt(0)
	v_cvt_pk_bf16_f32 v0, v38, v0
	global_store_dword v[4:5], v0, off offset:64
.LBB0_1171:
	s_or_b64 exec, exec, s[0:1]
	s_waitcnt lgkmcnt(0)
	s_nop 1
	v_mov_b32_dpp v0, v54 quad_perm:[1,0,3,2] row_mask:0xf bank_mask:0xf
	s_and_saveexec_b64 s[0:1], vcc
	s_cbranch_execz .LBB0_1173
	s_waitcnt lgkmcnt(0)
	v_cvt_pk_bf16_f32 v0, v54, v0
	global_store_dword v[4:5], v0, off offset:128
.LBB0_1173:
	s_or_b64 exec, exec, s[0:1]
	s_waitcnt lgkmcnt(0)
	s_nop 1
	v_mov_b32_dpp v0, v70 quad_perm:[1,0,3,2] row_mask:0xf bank_mask:0xf
	s_and_saveexec_b64 s[0:1], vcc
	s_cbranch_execz .LBB0_1175
	s_waitcnt lgkmcnt(0)
	v_cvt_pk_bf16_f32 v0, v70, v0
	global_store_dword v[4:5], v0, off offset:192
.LBB0_1175:
	s_or_b64 exec, exec, s[0:1]
	s_waitcnt lgkmcnt(0)
	v_add_u32_e32 v0, 11, v7
	s_movk_i32 s0, 0xc00
	v_mad_i64_i32 v[4:5], s[0:1], v0, s0, v[2:3]
	s_nop 1
	v_mov_b32_dpp v0, v23 quad_perm:[1,0,3,2] row_mask:0xf bank_mask:0xf
	s_and_saveexec_b64 s[0:1], vcc
	s_cbranch_execz .LBB0_1177
	s_waitcnt lgkmcnt(0)
	v_cvt_pk_bf16_f32 v0, v23, v0
	global_store_dword v[4:5], v0, off
.LBB0_1177:
	s_or_b64 exec, exec, s[0:1]
	s_waitcnt lgkmcnt(0)
	s_nop 1
	v_mov_b32_dpp v0, v39 quad_perm:[1,0,3,2] row_mask:0xf bank_mask:0xf
	s_and_saveexec_b64 s[0:1], vcc
	s_cbranch_execz .LBB0_1179
	s_waitcnt lgkmcnt(0)
	v_cvt_pk_bf16_f32 v0, v39, v0
	global_store_dword v[4:5], v0, off offset:64
.LBB0_1179:
	s_or_b64 exec, exec, s[0:1]
	s_waitcnt lgkmcnt(0)
	s_nop 1
	v_mov_b32_dpp v0, v55 quad_perm:[1,0,3,2] row_mask:0xf bank_mask:0xf
	s_and_saveexec_b64 s[0:1], vcc
	s_cbranch_execz .LBB0_1181
	s_waitcnt lgkmcnt(0)
	v_cvt_pk_bf16_f32 v0, v55, v0
	global_store_dword v[4:5], v0, off offset:128
.LBB0_1181:
	s_or_b64 exec, exec, s[0:1]
	s_waitcnt lgkmcnt(0)
	s_nop 1
	v_mov_b32_dpp v0, v71 quad_perm:[1,0,3,2] row_mask:0xf bank_mask:0xf
	s_and_saveexec_b64 s[0:1], vcc
	s_cbranch_execz .LBB0_1183
	s_waitcnt lgkmcnt(0)
	v_cvt_pk_bf16_f32 v0, v71, v0
	global_store_dword v[4:5], v0, off offset:192
.LBB0_1183:
	s_or_b64 exec, exec, s[0:1]
	s_waitcnt lgkmcnt(0)
	v_add_u32_e32 v0, 16, v7
	s_movk_i32 s0, 0xc00
	v_mad_i64_i32 v[4:5], s[0:1], v0, s0, v[2:3]
	s_nop 1
	v_mov_b32_dpp v0, v24 quad_perm:[1,0,3,2] row_mask:0xf bank_mask:0xf
	s_and_saveexec_b64 s[0:1], vcc
	s_cbranch_execz .LBB0_1185
	s_waitcnt lgkmcnt(0)
	v_cvt_pk_bf16_f32 v0, v24, v0
	global_store_dword v[4:5], v0, off
.LBB0_1185:
	s_or_b64 exec, exec, s[0:1]
	s_waitcnt lgkmcnt(0)
	s_nop 1
	v_mov_b32_dpp v0, v40 quad_perm:[1,0,3,2] row_mask:0xf bank_mask:0xf
	s_and_saveexec_b64 s[0:1], vcc
	s_cbranch_execz .LBB0_1187
	s_waitcnt lgkmcnt(0)
	v_cvt_pk_bf16_f32 v0, v40, v0
	global_store_dword v[4:5], v0, off offset:64
.LBB0_1187:
	s_or_b64 exec, exec, s[0:1]
	s_waitcnt lgkmcnt(0)
	s_nop 1
	v_mov_b32_dpp v0, v56 quad_perm:[1,0,3,2] row_mask:0xf bank_mask:0xf
	s_and_saveexec_b64 s[0:1], vcc
	s_cbranch_execz .LBB0_1189
	s_waitcnt lgkmcnt(0)
	v_cvt_pk_bf16_f32 v0, v56, v0
	global_store_dword v[4:5], v0, off offset:128
.LBB0_1189:
	s_or_b64 exec, exec, s[0:1]
	s_waitcnt lgkmcnt(0)
	s_nop 1
	v_mov_b32_dpp v0, v72 quad_perm:[1,0,3,2] row_mask:0xf bank_mask:0xf
	s_and_saveexec_b64 s[0:1], vcc
	s_cbranch_execz .LBB0_1191
	s_waitcnt lgkmcnt(0)
	v_cvt_pk_bf16_f32 v0, v72, v0
	global_store_dword v[4:5], v0, off offset:192
.LBB0_1191:
	s_or_b64 exec, exec, s[0:1]
	s_waitcnt lgkmcnt(0)
	v_add_u32_e32 v0, 17, v7
	s_movk_i32 s0, 0xc00
	v_mad_i64_i32 v[4:5], s[0:1], v0, s0, v[2:3]
	s_nop 1
	v_mov_b32_dpp v0, v25 quad_perm:[1,0,3,2] row_mask:0xf bank_mask:0xf
	s_and_saveexec_b64 s[0:1], vcc
	s_cbranch_execz .LBB0_1193
	s_waitcnt lgkmcnt(0)
	v_cvt_pk_bf16_f32 v0, v25, v0
	global_store_dword v[4:5], v0, off
.LBB0_1193:
	s_or_b64 exec, exec, s[0:1]
	s_waitcnt lgkmcnt(0)
	s_nop 1
	v_mov_b32_dpp v0, v41 quad_perm:[1,0,3,2] row_mask:0xf bank_mask:0xf
	s_and_saveexec_b64 s[0:1], vcc
	s_cbranch_execz .LBB0_1195
	s_waitcnt lgkmcnt(0)
	v_cvt_pk_bf16_f32 v0, v41, v0
	global_store_dword v[4:5], v0, off offset:64
.LBB0_1195:
	s_or_b64 exec, exec, s[0:1]
	s_waitcnt lgkmcnt(0)
	s_nop 1
	v_mov_b32_dpp v0, v57 quad_perm:[1,0,3,2] row_mask:0xf bank_mask:0xf
	s_and_saveexec_b64 s[0:1], vcc
	s_cbranch_execz .LBB0_1197
	s_waitcnt lgkmcnt(0)
	v_cvt_pk_bf16_f32 v0, v57, v0
	global_store_dword v[4:5], v0, off offset:128
.LBB0_1197:
	s_or_b64 exec, exec, s[0:1]
	s_waitcnt lgkmcnt(0)
	s_nop 1
	v_mov_b32_dpp v0, v73 quad_perm:[1,0,3,2] row_mask:0xf bank_mask:0xf
	s_and_saveexec_b64 s[0:1], vcc
	s_cbranch_execz .LBB0_1199
	s_waitcnt lgkmcnt(0)
	v_cvt_pk_bf16_f32 v0, v73, v0
	global_store_dword v[4:5], v0, off offset:192
.LBB0_1199:
	s_or_b64 exec, exec, s[0:1]
	s_waitcnt lgkmcnt(0)
	v_add_u32_e32 v0, 18, v7
	s_movk_i32 s0, 0xc00
	v_mad_i64_i32 v[4:5], s[0:1], v0, s0, v[2:3]
	s_nop 1
	v_mov_b32_dpp v0, v26 quad_perm:[1,0,3,2] row_mask:0xf bank_mask:0xf
	s_and_saveexec_b64 s[0:1], vcc
	s_cbranch_execz .LBB0_1201
	s_waitcnt lgkmcnt(0)
	v_cvt_pk_bf16_f32 v0, v26, v0
	global_store_dword v[4:5], v0, off
.LBB0_1201:
	s_or_b64 exec, exec, s[0:1]
	s_waitcnt lgkmcnt(0)
	s_nop 1
	v_mov_b32_dpp v0, v42 quad_perm:[1,0,3,2] row_mask:0xf bank_mask:0xf
	s_and_saveexec_b64 s[0:1], vcc
	s_cbranch_execz .LBB0_1203
	s_waitcnt lgkmcnt(0)
	v_cvt_pk_bf16_f32 v0, v42, v0
	global_store_dword v[4:5], v0, off offset:64
.LBB0_1203:
	s_or_b64 exec, exec, s[0:1]
	s_waitcnt lgkmcnt(0)
	s_nop 1
	v_mov_b32_dpp v0, v58 quad_perm:[1,0,3,2] row_mask:0xf bank_mask:0xf
	s_and_saveexec_b64 s[0:1], vcc
	s_cbranch_execz .LBB0_1205
	s_waitcnt lgkmcnt(0)
	v_cvt_pk_bf16_f32 v0, v58, v0
	global_store_dword v[4:5], v0, off offset:128
.LBB0_1205:
	s_or_b64 exec, exec, s[0:1]
	s_waitcnt lgkmcnt(0)
	s_nop 1
	v_mov_b32_dpp v0, v74 quad_perm:[1,0,3,2] row_mask:0xf bank_mask:0xf
	s_and_saveexec_b64 s[0:1], vcc
	s_cbranch_execz .LBB0_1207
	s_waitcnt lgkmcnt(0)
	v_cvt_pk_bf16_f32 v0, v74, v0
	global_store_dword v[4:5], v0, off offset:192
.LBB0_1207:
	s_or_b64 exec, exec, s[0:1]
	s_waitcnt lgkmcnt(0)
	v_add_u32_e32 v0, 19, v7
	s_movk_i32 s0, 0xc00
	v_mad_i64_i32 v[4:5], s[0:1], v0, s0, v[2:3]
	s_nop 1
	v_mov_b32_dpp v0, v27 quad_perm:[1,0,3,2] row_mask:0xf bank_mask:0xf
	s_and_saveexec_b64 s[0:1], vcc
	s_cbranch_execz .LBB0_1209
	s_waitcnt lgkmcnt(0)
	v_cvt_pk_bf16_f32 v0, v27, v0
	global_store_dword v[4:5], v0, off
.LBB0_1209:
	s_or_b64 exec, exec, s[0:1]
	s_waitcnt lgkmcnt(0)
	s_nop 1
	v_mov_b32_dpp v0, v43 quad_perm:[1,0,3,2] row_mask:0xf bank_mask:0xf
	s_and_saveexec_b64 s[0:1], vcc
	s_cbranch_execz .LBB0_1211
	s_waitcnt lgkmcnt(0)
	v_cvt_pk_bf16_f32 v0, v43, v0
	global_store_dword v[4:5], v0, off offset:64
.LBB0_1211:
	s_or_b64 exec, exec, s[0:1]
	s_waitcnt lgkmcnt(0)
	s_nop 1
	v_mov_b32_dpp v0, v59 quad_perm:[1,0,3,2] row_mask:0xf bank_mask:0xf
	s_and_saveexec_b64 s[0:1], vcc
	s_cbranch_execz .LBB0_1213
	s_waitcnt lgkmcnt(0)
	v_cvt_pk_bf16_f32 v0, v59, v0
	global_store_dword v[4:5], v0, off offset:128
.LBB0_1213:
	s_or_b64 exec, exec, s[0:1]
	s_waitcnt lgkmcnt(0)
	s_nop 1
	v_mov_b32_dpp v0, v75 quad_perm:[1,0,3,2] row_mask:0xf bank_mask:0xf
	s_and_saveexec_b64 s[0:1], vcc
	s_cbranch_execz .LBB0_1215
	s_waitcnt lgkmcnt(0)
	v_cvt_pk_bf16_f32 v0, v75, v0
	global_store_dword v[4:5], v0, off offset:192
.LBB0_1215:
	s_or_b64 exec, exec, s[0:1]
	s_waitcnt lgkmcnt(0)
	v_add_u32_e32 v0, 24, v7
	s_movk_i32 s0, 0xc00
	v_mad_i64_i32 v[4:5], s[0:1], v0, s0, v[2:3]
	s_nop 1
	v_mov_b32_dpp v0, v28 quad_perm:[1,0,3,2] row_mask:0xf bank_mask:0xf
	s_and_saveexec_b64 s[0:1], vcc
	s_cbranch_execz .LBB0_1217
	s_waitcnt lgkmcnt(0)
	v_cvt_pk_bf16_f32 v0, v28, v0
	global_store_dword v[4:5], v0, off
.LBB0_1217:
	s_or_b64 exec, exec, s[0:1]
	s_waitcnt lgkmcnt(0)
	s_nop 1
	v_mov_b32_dpp v0, v44 quad_perm:[1,0,3,2] row_mask:0xf bank_mask:0xf
	s_and_saveexec_b64 s[0:1], vcc
	s_cbranch_execz .LBB0_1219
	s_waitcnt lgkmcnt(0)
	v_cvt_pk_bf16_f32 v0, v44, v0
	global_store_dword v[4:5], v0, off offset:64
.LBB0_1219:
	s_or_b64 exec, exec, s[0:1]
	s_waitcnt lgkmcnt(0)
	s_nop 1
	v_mov_b32_dpp v0, v60 quad_perm:[1,0,3,2] row_mask:0xf bank_mask:0xf
	s_and_saveexec_b64 s[0:1], vcc
	s_cbranch_execz .LBB0_1221
	s_waitcnt lgkmcnt(0)
	v_cvt_pk_bf16_f32 v0, v60, v0
	global_store_dword v[4:5], v0, off offset:128
.LBB0_1221:
	s_or_b64 exec, exec, s[0:1]
	s_waitcnt lgkmcnt(0)
	s_nop 1
	v_mov_b32_dpp v0, v76 quad_perm:[1,0,3,2] row_mask:0xf bank_mask:0xf
	s_and_saveexec_b64 s[0:1], vcc
	s_cbranch_execz .LBB0_1223
	s_waitcnt lgkmcnt(0)
	v_cvt_pk_bf16_f32 v0, v76, v0
	global_store_dword v[4:5], v0, off offset:192
.LBB0_1223:
	s_or_b64 exec, exec, s[0:1]
	s_waitcnt lgkmcnt(0)
	v_add_u32_e32 v0, 25, v7
	s_movk_i32 s0, 0xc00
	v_mad_i64_i32 v[4:5], s[0:1], v0, s0, v[2:3]
	s_nop 1
	v_mov_b32_dpp v0, v29 quad_perm:[1,0,3,2] row_mask:0xf bank_mask:0xf
	s_and_saveexec_b64 s[0:1], vcc
	s_cbranch_execz .LBB0_1225
	s_waitcnt lgkmcnt(0)
	v_cvt_pk_bf16_f32 v0, v29, v0
	global_store_dword v[4:5], v0, off
.LBB0_1225:
	s_or_b64 exec, exec, s[0:1]
	s_waitcnt lgkmcnt(0)
	s_nop 1
	v_mov_b32_dpp v0, v45 quad_perm:[1,0,3,2] row_mask:0xf bank_mask:0xf
	s_and_saveexec_b64 s[0:1], vcc
	s_cbranch_execz .LBB0_1227
	s_waitcnt lgkmcnt(0)
	v_cvt_pk_bf16_f32 v0, v45, v0
	global_store_dword v[4:5], v0, off offset:64
.LBB0_1227:
	s_or_b64 exec, exec, s[0:1]
	s_waitcnt lgkmcnt(0)
	s_nop 1
	v_mov_b32_dpp v0, v61 quad_perm:[1,0,3,2] row_mask:0xf bank_mask:0xf
	s_and_saveexec_b64 s[0:1], vcc
	s_cbranch_execz .LBB0_1229
	s_waitcnt lgkmcnt(0)
	v_cvt_pk_bf16_f32 v0, v61, v0
	global_store_dword v[4:5], v0, off offset:128
.LBB0_1229:
	s_or_b64 exec, exec, s[0:1]
	s_waitcnt lgkmcnt(0)
	s_nop 1
	v_mov_b32_dpp v0, v77 quad_perm:[1,0,3,2] row_mask:0xf bank_mask:0xf
	s_and_saveexec_b64 s[0:1], vcc
	s_cbranch_execz .LBB0_1231
	s_waitcnt lgkmcnt(0)
	v_cvt_pk_bf16_f32 v0, v77, v0
	global_store_dword v[4:5], v0, off offset:192
.LBB0_1231:
	s_or_b64 exec, exec, s[0:1]
	s_waitcnt lgkmcnt(0)
	v_add_u32_e32 v0, 26, v7
	s_movk_i32 s0, 0xc00
	v_mad_i64_i32 v[4:5], s[0:1], v0, s0, v[2:3]
	s_nop 1
	v_mov_b32_dpp v0, v30 quad_perm:[1,0,3,2] row_mask:0xf bank_mask:0xf
	s_and_saveexec_b64 s[0:1], vcc
	s_cbranch_execz .LBB0_1233
	s_waitcnt lgkmcnt(0)
	v_cvt_pk_bf16_f32 v0, v30, v0
	global_store_dword v[4:5], v0, off
.LBB0_1233:
	s_or_b64 exec, exec, s[0:1]
	s_waitcnt lgkmcnt(0)
	s_nop 1
	v_mov_b32_dpp v0, v46 quad_perm:[1,0,3,2] row_mask:0xf bank_mask:0xf
	s_and_saveexec_b64 s[0:1], vcc
	s_cbranch_execz .LBB0_1235
	s_waitcnt lgkmcnt(0)
	v_cvt_pk_bf16_f32 v0, v46, v0
	global_store_dword v[4:5], v0, off offset:64
.LBB0_1235:
	s_or_b64 exec, exec, s[0:1]
	s_waitcnt lgkmcnt(0)
	s_nop 1
	v_mov_b32_dpp v0, v62 quad_perm:[1,0,3,2] row_mask:0xf bank_mask:0xf
	s_and_saveexec_b64 s[0:1], vcc
	s_cbranch_execz .LBB0_1237
	s_waitcnt lgkmcnt(0)
	v_cvt_pk_bf16_f32 v0, v62, v0
	global_store_dword v[4:5], v0, off offset:128
.LBB0_1237:
	s_or_b64 exec, exec, s[0:1]
	s_waitcnt lgkmcnt(0)
	s_nop 1
	v_mov_b32_dpp v0, v78 quad_perm:[1,0,3,2] row_mask:0xf bank_mask:0xf
	s_and_saveexec_b64 s[0:1], vcc
	s_cbranch_execz .LBB0_1239
	s_waitcnt lgkmcnt(0)
	v_cvt_pk_bf16_f32 v0, v78, v0
	global_store_dword v[4:5], v0, off offset:192
.LBB0_1239:
	s_or_b64 exec, exec, s[0:1]
	s_waitcnt lgkmcnt(0)
	v_add_u32_e32 v0, 27, v7
	s_movk_i32 s0, 0xc00
	v_mad_i64_i32 v[2:3], s[0:1], v0, s0, v[2:3]
	s_nop 1
	v_mov_b32_dpp v0, v31 quad_perm:[1,0,3,2] row_mask:0xf bank_mask:0xf
	s_and_saveexec_b64 s[0:1], vcc
	s_cbranch_execz .LBB0_1241
	s_waitcnt lgkmcnt(0)
	v_cvt_pk_bf16_f32 v0, v31, v0
	global_store_dword v[2:3], v0, off
.LBB0_1241:
	s_or_b64 exec, exec, s[0:1]
	s_waitcnt lgkmcnt(0)
	s_nop 1
	v_mov_b32_dpp v0, v47 quad_perm:[1,0,3,2] row_mask:0xf bank_mask:0xf
	s_and_saveexec_b64 s[0:1], vcc
	s_cbranch_execz .LBB0_1243
	s_waitcnt lgkmcnt(0)
	v_cvt_pk_bf16_f32 v0, v47, v0
	global_store_dword v[2:3], v0, off offset:64
.LBB0_1243:
	s_or_b64 exec, exec, s[0:1]
	s_waitcnt lgkmcnt(0)
	s_nop 1
	v_mov_b32_dpp v0, v63 quad_perm:[1,0,3,2] row_mask:0xf bank_mask:0xf
	s_and_saveexec_b64 s[0:1], vcc
	s_cbranch_execz .LBB0_1245
	s_waitcnt lgkmcnt(0)
	v_cvt_pk_bf16_f32 v0, v63, v0
	global_store_dword v[2:3], v0, off offset:128
.LBB0_1245:
	s_or_b64 exec, exec, s[0:1]
	s_waitcnt lgkmcnt(0)
	s_nop 1
	v_mov_b32_dpp v0, v79 quad_perm:[1,0,3,2] row_mask:0xf bank_mask:0xf
	s_and_saveexec_b64 s[0:1], vcc
	s_xor_b64 s[0:1], exec, s[0:1]
	s_cbranch_execz .LBB0_1247
	s_waitcnt lgkmcnt(0)
	v_cvt_pk_bf16_f32 v0, v79, v0
	global_store_dword v[2:3], v0, off offset:192

.LBB0_1294:
	s_or_b64 exec, exec, s[0:1]
	v_readlane_b32 s0, v254, 53
	s_waitcnt lgkmcnt(0)
	v_and_b32_e32 v14, 64, v231
	v_add_u32_e32 v14, 64, v14
	v_lshl_add_u32 v0, v175, 4, s0
	ds_read_b128 v[80:83], v0
	ds_read_b128 v[10:13], v0 offset:32
	v_readlane_b32 s2, v253, 33
	v_readlane_b32 s3, v253, 34
	v_lshlrev_b32_e32 v86, 2, v175
	s_waitcnt vmcnt(4) lgkmcnt(1)
	v_div_scale_f32 v2, s[0:1], v80, v80, 1.0
	s_waitcnt vmcnt(3)
	v_rcp_f32_e32 v3, v2
	s_waitcnt vmcnt(2)
	v_div_scale_f32 v4, vcc, 1.0, v80, 1.0
	v_readlane_b32 s0, v255, 24
	s_waitcnt vmcnt(1)
	v_fma_f32 v5, -v2, v3, 1.0
	v_fmac_f32_e32 v3, v5, v3
	v_mul_f32_e32 v5, v4, v3
	s_waitcnt vmcnt(0)
	v_fma_f32 v6, -v2, v5, v4
	v_fmac_f32_e32 v5, v6, v3
	v_fma_f32 v2, -v2, v5, v4
	v_div_fmas_f32 v2, v2, v3, v5
	v_div_fixup_f32 v87, v2, v80, 1.0
	ds_read_b128 v[6:9], v0 offset:64
	ds_read_b128 v[2:5], v0 offset:96
	v_xor_b32_e32 v0, 1, v231
	v_readlane_b32 s1, v255, 25
	s_add_i32 s0, s0, s55
	v_cmp_lt_i32_e32 vcc, v0, v14
	s_mul_hi_i32 s1, s0, 0xc00
	s_mulk_i32 s0, 0xc00
	v_cndmask_b32_e32 v0, v231, v0, vcc
	s_add_u32 s0, s2, s0
	v_lshlrev_b32_e32 v80, 2, v0
	v_mul_f32_e32 v64, v64, v87
	s_addc_u32 s1, s3, s1
	s_lshl_b32 s2, s18, 1
	s_nop 1
	v_mov_b32_dpp v88, v64 quad_perm:[1,0,3,2] row_mask:0xf bank_mask:0xf
	s_add_u32 s0, s0, s2
	v_and_b32_e32 v0, 1, v162
	s_addc_u32 s1, s1, 0
	v_cmp_eq_u32_e64 s[34:35], 0, v0
	v_lshlrev_b32_e32 v0, 1, v174
	v_lshl_add_u64 v[14:15], s[0:1], 0, v[0:1]
	s_movk_i32 s0, 0xc00
	v_mad_i64_i32 v[84:85], s[0:1], v86, s0, v[14:15]
	s_and_saveexec_b64 s[0:1], s[34:35]
	s_cbranch_execz .LBB0_1296
	s_waitcnt lgkmcnt(0)
	v_cvt_pk_bf16_f32 v0, v64, v88
	global_store_dword v[84:85], v0, off
.LBB0_1296:
	s_or_b64 exec, exec, s[0:1]
	v_mul_f32_e32 v0, v48, v87
	s_nop 1
	v_mov_b32_dpp v48, v0 quad_perm:[1,0,3,2] row_mask:0xf bank_mask:0xf
	s_and_saveexec_b64 s[0:1], s[34:35]
	s_cbranch_execz .LBB0_1298
	s_waitcnt lgkmcnt(0)
	v_cvt_pk_bf16_f32 v0, v0, v48
	global_store_dword v[84:85], v0, off offset:64
.LBB0_1298:
	s_or_b64 exec, exec, s[0:1]
	v_mul_f32_e32 v0, v32, v87
	s_nop 1
	v_mov_b32_dpp v32, v0 quad_perm:[1,0,3,2] row_mask:0xf bank_mask:0xf
	s_and_saveexec_b64 s[0:1], s[34:35]
	s_cbranch_execz .LBB0_1300
	s_waitcnt lgkmcnt(0)
	v_cvt_pk_bf16_f32 v0, v0, v32
	global_store_dword v[84:85], v0, off offset:128
.LBB0_1300:
	s_or_b64 exec, exec, s[0:1]
	v_mul_f32_e32 v0, v16, v87
	s_nop 1
	v_mov_b32_dpp v16, v0 quad_perm:[1,0,3,2] row_mask:0xf bank_mask:0xf
	s_and_saveexec_b64 s[0:1], s[34:35]
	s_cbranch_execz .LBB0_1302
	s_waitcnt lgkmcnt(0)
	v_cvt_pk_bf16_f32 v0, v0, v16
	global_store_dword v[84:85], v0, off offset:192
.LBB0_1302:
	s_or_b64 exec, exec, s[0:1]
	v_div_scale_f32 v0, s[0:1], v81, v81, 1.0
	s_waitcnt lgkmcnt(0)
	v_rcp_f32_e32 v16, v0
	v_div_scale_f32 v32, vcc, 1.0, v81, 1.0
	s_movk_i32 s0, 0xc00
	v_fma_f32 v48, -v0, v16, 1.0
	v_fmac_f32_e32 v16, v48, v16
	v_mul_f32_e32 v48, v32, v16
	v_fma_f32 v64, -v0, v48, v32
	v_fmac_f32_e32 v48, v64, v16
	v_fma_f32 v0, -v0, v48, v32
	v_div_fmas_f32 v0, v0, v16, v48
	v_div_fixup_f32 v0, v0, v81, 1.0
	v_mul_f32_e32 v16, v65, v0
	s_nop 1
	v_mov_b32_dpp v32, v16 quad_perm:[1,0,3,2] row_mask:0xf bank_mask:0xf
	v_or_b32_e32 v48, 1, v86
	v_mad_i64_i32 v[64:65], s[0:1], v48, s0, v[14:15]
	s_and_saveexec_b64 s[0:1], s[34:35]
	s_cbranch_execz .LBB0_1304
	s_waitcnt lgkmcnt(0)
	v_cvt_pk_bf16_f32 v16, v16, v32
	global_store_dword v[64:65], v16, off
.LBB0_1304:
	s_or_b64 exec, exec, s[0:1]
	v_mul_f32_e32 v16, v49, v0
	s_waitcnt lgkmcnt(0)
	s_nop 1
	v_mov_b32_dpp v32, v16 quad_perm:[1,0,3,2] row_mask:0xf bank_mask:0xf
	s_and_saveexec_b64 s[0:1], s[34:35]
	s_cbranch_execz .LBB0_1306
	s_waitcnt lgkmcnt(0)
	v_cvt_pk_bf16_f32 v16, v16, v32
	global_store_dword v[64:65], v16, off offset:64
.LBB0_1306:
	s_or_b64 exec, exec, s[0:1]
	v_mul_f32_e32 v16, v33, v0
	s_waitcnt lgkmcnt(0)
	s_nop 1
	v_mov_b32_dpp v32, v16 quad_perm:[1,0,3,2] row_mask:0xf bank_mask:0xf
	s_and_saveexec_b64 s[0:1], s[34:35]
	s_cbranch_execz .LBB0_1308
	s_waitcnt lgkmcnt(0)
	v_cvt_pk_bf16_f32 v16, v16, v32
	global_store_dword v[64:65], v16, off offset:128
.LBB0_1308:
	s_or_b64 exec, exec, s[0:1]
	v_mul_f32_e32 v0, v17, v0
	s_nop 1
	v_mov_b32_dpp v16, v0 quad_perm:[1,0,3,2] row_mask:0xf bank_mask:0xf
	s_and_saveexec_b64 s[0:1], s[34:35]
	s_cbranch_execz .LBB0_1310
	s_waitcnt lgkmcnt(0)
	v_cvt_pk_bf16_f32 v0, v0, v16
	global_store_dword v[64:65], v0, off offset:192
.LBB0_1310:
	s_or_b64 exec, exec, s[0:1]
	v_div_scale_f32 v0, s[0:1], v82, v82, 1.0
	s_waitcnt lgkmcnt(0)
	v_rcp_f32_e32 v16, v0
	v_div_scale_f32 v17, vcc, 1.0, v82, 1.0
	s_movk_i32 s0, 0xc00
	v_fma_f32 v32, -v0, v16, 1.0
	v_fmac_f32_e32 v16, v32, v16
	v_mul_f32_e32 v32, v17, v16
	v_fma_f32 v33, -v0, v32, v17
	v_fmac_f32_e32 v32, v33, v16
	v_fma_f32 v0, -v0, v32, v17
	v_div_fmas_f32 v0, v0, v16, v32
	v_div_fixup_f32 v0, v0, v82, 1.0
	v_mul_f32_e32 v32, v66, v0
	s_nop 1
	v_mov_b32_dpp v33, v32 quad_perm:[1,0,3,2] row_mask:0xf bank_mask:0xf
	v_or_b32_e32 v16, 2, v86
	v_mad_i64_i32 v[16:17], s[0:1], v16, s0, v[14:15]
	s_and_saveexec_b64 s[0:1], s[34:35]
	s_cbranch_execz .LBB0_1312
	s_waitcnt lgkmcnt(0)
	v_cvt_pk_bf16_f32 v32, v32, v33
	global_store_dword v[16:17], v32, off
.LBB0_1312:
	s_or_b64 exec, exec, s[0:1]
	v_mul_f32_e32 v32, v50, v0
	s_waitcnt lgkmcnt(0)
	s_nop 1
	v_mov_b32_dpp v33, v32 quad_perm:[1,0,3,2] row_mask:0xf bank_mask:0xf
	s_and_saveexec_b64 s[0:1], s[34:35]
	s_cbranch_execz .LBB0_1314
	s_waitcnt lgkmcnt(0)
	v_cvt_pk_bf16_f32 v32, v32, v33
	global_store_dword v[16:17], v32, off offset:64
.LBB0_1314:
	s_or_b64 exec, exec, s[0:1]
	v_mul_f32_e32 v32, v34, v0
	s_waitcnt lgkmcnt(0)
	s_nop 1
	v_mov_b32_dpp v33, v32 quad_perm:[1,0,3,2] row_mask:0xf bank_mask:0xf
	s_and_saveexec_b64 s[0:1], s[34:35]
	s_cbranch_execz .LBB0_1316
	s_waitcnt lgkmcnt(0)
	v_cvt_pk_bf16_f32 v32, v32, v33
	global_store_dword v[16:17], v32, off offset:128
.LBB0_1316:
	s_or_b64 exec, exec, s[0:1]
	v_mul_f32_e32 v0, v18, v0
	s_nop 1
	v_mov_b32_dpp v18, v0 quad_perm:[1,0,3,2] row_mask:0xf bank_mask:0xf
	s_and_saveexec_b64 s[0:1], s[34:35]
	s_cbranch_execz .LBB0_1318
	s_waitcnt lgkmcnt(0)
	v_cvt_pk_bf16_f32 v0, v0, v18
	global_store_dword v[16:17], v0, off offset:192
.LBB0_1318:
	s_or_b64 exec, exec, s[0:1]
	v_div_scale_f32 v0, s[0:1], v83, v83, 1.0
	v_rcp_f32_e32 v16, v0
	v_div_scale_f32 v17, vcc, 1.0, v83, 1.0
	s_movk_i32 s0, 0xc00
	s_waitcnt lgkmcnt(0)
	v_fma_f32 v18, -v0, v16, 1.0
	v_fmac_f32_e32 v16, v18, v16
	v_mul_f32_e32 v18, v17, v16
	v_fma_f32 v32, -v0, v18, v17
	v_fmac_f32_e32 v18, v32, v16
	v_fma_f32 v0, -v0, v18, v17
	v_div_fmas_f32 v0, v0, v16, v18
	v_div_fixup_f32 v0, v0, v83, 1.0
	v_mul_f32_e32 v18, v67, v0
	s_nop 1
	v_mov_b32_dpp v32, v18 quad_perm:[1,0,3,2] row_mask:0xf bank_mask:0xf
	v_or_b32_e32 v16, 3, v86
	v_mad_i64_i32 v[16:17], s[0:1], v16, s0, v[14:15]
	s_and_saveexec_b64 s[0:1], s[34:35]
	s_cbranch_execz .LBB0_1320
	s_waitcnt lgkmcnt(0)
	v_cvt_pk_bf16_f32 v18, v18, v32
	global_store_dword v[16:17], v18, off
.LBB0_1320:
	s_or_b64 exec, exec, s[0:1]
	v_mul_f32_e32 v18, v51, v0
	s_waitcnt lgkmcnt(0)
	s_nop 1
	v_mov_b32_dpp v32, v18 quad_perm:[1,0,3,2] row_mask:0xf bank_mask:0xf
	s_and_saveexec_b64 s[0:1], s[34:35]
	s_cbranch_execz .LBB0_1322
	s_waitcnt lgkmcnt(0)
	v_cvt_pk_bf16_f32 v18, v18, v32
	global_store_dword v[16:17], v18, off offset:64
.LBB0_1322:
	s_or_b64 exec, exec, s[0:1]
	v_mul_f32_e32 v18, v35, v0
	s_waitcnt lgkmcnt(0)
	s_nop 1
	v_mov_b32_dpp v32, v18 quad_perm:[1,0,3,2] row_mask:0xf bank_mask:0xf
	s_and_saveexec_b64 s[0:1], s[34:35]
	s_cbranch_execz .LBB0_1324
	s_waitcnt lgkmcnt(0)
	v_cvt_pk_bf16_f32 v18, v18, v32
	global_store_dword v[16:17], v18, off offset:128
.LBB0_1324:
	s_or_b64 exec, exec, s[0:1]
	v_mul_f32_e32 v0, v19, v0
	s_nop 1
	v_mov_b32_dpp v18, v0 quad_perm:[1,0,3,2] row_mask:0xf bank_mask:0xf
	s_and_saveexec_b64 s[0:1], s[34:35]
	s_cbranch_execz .LBB0_1326
	s_waitcnt lgkmcnt(0)
	v_cvt_pk_bf16_f32 v0, v0, v18
	global_store_dword v[16:17], v0, off offset:192
.LBB0_1326:
	s_or_b64 exec, exec, s[0:1]
	v_div_scale_f32 v0, s[0:1], v10, v10, 1.0
	v_rcp_f32_e32 v16, v0
	v_div_scale_f32 v17, vcc, 1.0, v10, 1.0
	s_movk_i32 s0, 0xc00
	s_waitcnt lgkmcnt(0)
	v_fma_f32 v18, -v0, v16, 1.0
	v_fmac_f32_e32 v16, v18, v16
	v_mul_f32_e32 v18, v17, v16
	v_fma_f32 v19, -v0, v18, v17
	v_fmac_f32_e32 v18, v19, v16
	v_fma_f32 v0, -v0, v18, v17
	v_div_fmas_f32 v0, v0, v16, v18
	v_div_fixup_f32 v0, v0, v10, 1.0
	v_mul_f32_e32 v10, v68, v0
	s_nop 1
	v_mov_b32_dpp v18, v10 quad_perm:[1,0,3,2] row_mask:0xf bank_mask:0xf
	v_add_u32_e32 v16, 8, v86
	v_mad_i64_i32 v[16:17], s[0:1], v16, s0, v[14:15]
	s_and_saveexec_b64 s[0:1], s[34:35]
	s_cbranch_execz .LBB0_1328
	s_waitcnt lgkmcnt(0)
	v_cvt_pk_bf16_f32 v10, v10, v18
	global_store_dword v[16:17], v10, off
.LBB0_1328:
	s_or_b64 exec, exec, s[0:1]
	v_mul_f32_e32 v10, v52, v0
	s_waitcnt lgkmcnt(0)
	s_nop 1
	v_mov_b32_dpp v18, v10 quad_perm:[1,0,3,2] row_mask:0xf bank_mask:0xf
	s_and_saveexec_b64 s[0:1], s[34:35]
	s_cbranch_execz .LBB0_1330
	s_waitcnt lgkmcnt(0)
	v_cvt_pk_bf16_f32 v10, v10, v18
	global_store_dword v[16:17], v10, off offset:64
.LBB0_1330:
	s_or_b64 exec, exec, s[0:1]
	v_mul_f32_e32 v10, v36, v0
	s_waitcnt lgkmcnt(0)
	s_nop 1
	v_mov_b32_dpp v18, v10 quad_perm:[1,0,3,2] row_mask:0xf bank_mask:0xf
	s_and_saveexec_b64 s[0:1], s[34:35]
	s_cbranch_execz .LBB0_1332
	s_waitcnt lgkmcnt(0)
	v_cvt_pk_bf16_f32 v10, v10, v18
	global_store_dword v[16:17], v10, off offset:128
.LBB0_1332:
	s_or_b64 exec, exec, s[0:1]
	v_mul_f32_e32 v0, v20, v0
	s_nop 1
	v_mov_b32_dpp v10, v0 quad_perm:[1,0,3,2] row_mask:0xf bank_mask:0xf
	s_and_saveexec_b64 s[0:1], s[34:35]
	s_cbranch_execz .LBB0_1334
	s_waitcnt lgkmcnt(0)
	v_cvt_pk_bf16_f32 v0, v0, v10
	global_store_dword v[16:17], v0, off offset:192
.LBB0_1334:
	s_or_b64 exec, exec, s[0:1]
	v_div_scale_f32 v0, s[0:1], v11, v11, 1.0
	s_waitcnt lgkmcnt(0)
	v_rcp_f32_e32 v10, v0
	v_div_scale_f32 v16, vcc, 1.0, v11, 1.0
	s_movk_i32 s0, 0xc00
	v_fma_f32 v17, -v0, v10, 1.0
	v_fmac_f32_e32 v10, v17, v10
	v_mul_f32_e32 v17, v16, v10
	v_fma_f32 v18, -v0, v17, v16
	v_fmac_f32_e32 v17, v18, v10
	v_fma_f32 v0, -v0, v17, v16
	v_div_fmas_f32 v0, v0, v10, v17
	v_div_fixup_f32 v0, v0, v11, 1.0
	v_mul_f32_e32 v16, v69, v0
	s_nop 1
	v_mov_b32_dpp v17, v16 quad_perm:[1,0,3,2] row_mask:0xf bank_mask:0xf
	v_add_u32_e32 v10, 9, v86
	v_mad_i64_i32 v[10:11], s[0:1], v10, s0, v[14:15]
	s_and_saveexec_b64 s[0:1], s[34:35]
	s_cbranch_execz .LBB0_1336
	s_waitcnt lgkmcnt(0)
	v_cvt_pk_bf16_f32 v16, v16, v17
	global_store_dword v[10:11], v16, off
.LBB0_1336:
	s_or_b64 exec, exec, s[0:1]
	v_mul_f32_e32 v16, v53, v0
	s_waitcnt lgkmcnt(0)
	s_nop 1
	v_mov_b32_dpp v17, v16 quad_perm:[1,0,3,2] row_mask:0xf bank_mask:0xf
	s_and_saveexec_b64 s[0:1], s[34:35]
	s_cbranch_execz .LBB0_1338
	s_waitcnt lgkmcnt(0)
	v_cvt_pk_bf16_f32 v16, v16, v17
	global_store_dword v[10:11], v16, off offset:64
.LBB0_1338:
	s_or_b64 exec, exec, s[0:1]
	v_mul_f32_e32 v16, v37, v0
	s_waitcnt lgkmcnt(0)
	s_nop 1
	v_mov_b32_dpp v17, v16 quad_perm:[1,0,3,2] row_mask:0xf bank_mask:0xf
	s_and_saveexec_b64 s[0:1], s[34:35]
	s_cbranch_execz .LBB0_1340
	s_waitcnt lgkmcnt(0)
	v_cvt_pk_bf16_f32 v16, v16, v17
	global_store_dword v[10:11], v16, off offset:128
.LBB0_1340:
	s_or_b64 exec, exec, s[0:1]
	v_mul_f32_e32 v0, v21, v0
	s_nop 1
	v_mov_b32_dpp v16, v0 quad_perm:[1,0,3,2] row_mask:0xf bank_mask:0xf
	s_and_saveexec_b64 s[0:1], s[34:35]
	s_cbranch_execz .LBB0_1342
	s_waitcnt lgkmcnt(0)
	v_cvt_pk_bf16_f32 v0, v0, v16
	global_store_dword v[10:11], v0, off offset:192
.LBB0_1342:
	s_or_b64 exec, exec, s[0:1]
	v_div_scale_f32 v0, s[0:1], v12, v12, 1.0
	v_rcp_f32_e32 v10, v0
	v_div_scale_f32 v11, vcc, 1.0, v12, 1.0
	s_movk_i32 s0, 0xc00
	s_waitcnt lgkmcnt(0)
	v_fma_f32 v16, -v0, v10, 1.0
	v_fmac_f32_e32 v10, v16, v10
	v_mul_f32_e32 v16, v11, v10
	v_fma_f32 v17, -v0, v16, v11
	v_fmac_f32_e32 v16, v17, v10
	v_fma_f32 v0, -v0, v16, v11
	v_div_fmas_f32 v0, v0, v10, v16
	v_div_fixup_f32 v0, v0, v12, 1.0
	v_mul_f32_e32 v12, v70, v0
	s_nop 1
	v_mov_b32_dpp v16, v12 quad_perm:[1,0,3,2] row_mask:0xf bank_mask:0xf
	v_add_u32_e32 v10, 10, v86
	v_mad_i64_i32 v[10:11], s[0:1], v10, s0, v[14:15]
	s_and_saveexec_b64 s[0:1], s[34:35]
	s_cbranch_execz .LBB0_1344
	s_waitcnt lgkmcnt(0)
	v_cvt_pk_bf16_f32 v12, v12, v16
	global_store_dword v[10:11], v12, off
.LBB0_1344:
	s_or_b64 exec, exec, s[0:1]
	v_mul_f32_e32 v12, v54, v0
	s_waitcnt lgkmcnt(0)
	s_nop 1
	v_mov_b32_dpp v16, v12 quad_perm:[1,0,3,2] row_mask:0xf bank_mask:0xf
	s_and_saveexec_b64 s[0:1], s[34:35]
	s_cbranch_execz .LBB0_1346
	s_waitcnt lgkmcnt(0)
	v_cvt_pk_bf16_f32 v12, v12, v16
	global_store_dword v[10:11], v12, off offset:64
.LBB0_1346:
	s_or_b64 exec, exec, s[0:1]
	v_mul_f32_e32 v12, v38, v0
	s_waitcnt lgkmcnt(0)
	s_nop 1
	v_mov_b32_dpp v16, v12 quad_perm:[1,0,3,2] row_mask:0xf bank_mask:0xf
	s_and_saveexec_b64 s[0:1], s[34:35]
	s_cbranch_execz .LBB0_1348
	s_waitcnt lgkmcnt(0)
	v_cvt_pk_bf16_f32 v12, v12, v16
	global_store_dword v[10:11], v12, off offset:128
.LBB0_1348:
	s_or_b64 exec, exec, s[0:1]
	v_mul_f32_e32 v0, v22, v0
	s_nop 1
	v_mov_b32_dpp v12, v0 quad_perm:[1,0,3,2] row_mask:0xf bank_mask:0xf
	s_and_saveexec_b64 s[0:1], s[34:35]
	s_cbranch_execz .LBB0_1350
	s_waitcnt lgkmcnt(0)
	v_cvt_pk_bf16_f32 v0, v0, v12
	global_store_dword v[10:11], v0, off offset:192
.LBB0_1350:
	s_or_b64 exec, exec, s[0:1]
	v_div_scale_f32 v0, s[0:1], v13, v13, 1.0
	v_rcp_f32_e32 v10, v0
	v_div_scale_f32 v11, vcc, 1.0, v13, 1.0
	s_movk_i32 s0, 0xc00
	s_waitcnt lgkmcnt(0)
	v_fma_f32 v12, -v0, v10, 1.0
	v_fmac_f32_e32 v10, v12, v10
	v_mul_f32_e32 v12, v11, v10
	v_fma_f32 v16, -v0, v12, v11
	v_fmac_f32_e32 v12, v16, v10
	v_fma_f32 v0, -v0, v12, v11
	v_div_fmas_f32 v0, v0, v10, v12
	v_div_fixup_f32 v0, v0, v13, 1.0
	v_mul_f32_e32 v12, v71, v0
	s_nop 1
	v_mov_b32_dpp v13, v12 quad_perm:[1,0,3,2] row_mask:0xf bank_mask:0xf
	v_add_u32_e32 v10, 11, v86
	v_mad_i64_i32 v[10:11], s[0:1], v10, s0, v[14:15]
	s_and_saveexec_b64 s[0:1], s[34:35]
	s_cbranch_execz .LBB0_1352
	s_waitcnt lgkmcnt(0)
	v_cvt_pk_bf16_f32 v12, v12, v13
	global_store_dword v[10:11], v12, off
.LBB0_1352:
	s_or_b64 exec, exec, s[0:1]
	v_mul_f32_e32 v12, v55, v0
	s_waitcnt lgkmcnt(0)
	s_nop 1
	v_mov_b32_dpp v13, v12 quad_perm:[1,0,3,2] row_mask:0xf bank_mask:0xf
	s_and_saveexec_b64 s[0:1], s[34:35]
	s_cbranch_execz .LBB0_1354
	s_waitcnt lgkmcnt(0)
	v_cvt_pk_bf16_f32 v12, v12, v13
	global_store_dword v[10:11], v12, off offset:64
.LBB0_1354:
	s_or_b64 exec, exec, s[0:1]
	v_mul_f32_e32 v12, v39, v0
	s_waitcnt lgkmcnt(0)
	s_nop 1
	v_mov_b32_dpp v13, v12 quad_perm:[1,0,3,2] row_mask:0xf bank_mask:0xf
	s_and_saveexec_b64 s[0:1], s[34:35]
	s_cbranch_execz .LBB0_1356
	s_waitcnt lgkmcnt(0)
	v_cvt_pk_bf16_f32 v12, v12, v13
	global_store_dword v[10:11], v12, off offset:128
.LBB0_1356:
	s_or_b64 exec, exec, s[0:1]
	v_mul_f32_e32 v0, v23, v0
	s_nop 1
	v_mov_b32_dpp v12, v0 quad_perm:[1,0,3,2] row_mask:0xf bank_mask:0xf
	s_and_saveexec_b64 s[0:1], s[34:35]
	s_cbranch_execz .LBB0_1358
	s_waitcnt lgkmcnt(0)
	v_cvt_pk_bf16_f32 v0, v0, v12
	global_store_dword v[10:11], v0, off offset:192
.LBB0_1358:
	s_or_b64 exec, exec, s[0:1]
	v_div_scale_f32 v0, s[0:1], v6, v6, 1.0
	v_rcp_f32_e32 v10, v0
	v_div_scale_f32 v11, vcc, 1.0, v6, 1.0
	s_movk_i32 s0, 0xc00
	s_waitcnt lgkmcnt(0)
	v_fma_f32 v12, -v0, v10, 1.0
	v_fmac_f32_e32 v10, v12, v10
	v_mul_f32_e32 v12, v11, v10
	v_fma_f32 v13, -v0, v12, v11
	v_fmac_f32_e32 v12, v13, v10
	v_fma_f32 v0, -v0, v12, v11
	v_div_fmas_f32 v0, v0, v10, v12
	v_div_fixup_f32 v0, v0, v6, 1.0
	v_mul_f32_e32 v6, v72, v0
	s_nop 1
	v_mov_b32_dpp v12, v6 quad_perm:[1,0,3,2] row_mask:0xf bank_mask:0xf
	v_add_u32_e32 v10, 16, v86
	v_mad_i64_i32 v[10:11], s[0:1], v10, s0, v[14:15]
	s_and_saveexec_b64 s[0:1], s[34:35]
	s_cbranch_execz .LBB0_1360
	s_waitcnt lgkmcnt(0)
	v_cvt_pk_bf16_f32 v6, v6, v12
	global_store_dword v[10:11], v6, off
.LBB0_1360:
	s_or_b64 exec, exec, s[0:1]
	v_mul_f32_e32 v6, v56, v0
	s_waitcnt lgkmcnt(0)
	s_nop 1
	v_mov_b32_dpp v12, v6 quad_perm:[1,0,3,2] row_mask:0xf bank_mask:0xf
	s_and_saveexec_b64 s[0:1], s[34:35]
	s_cbranch_execz .LBB0_1362
	s_waitcnt lgkmcnt(0)
	v_cvt_pk_bf16_f32 v6, v6, v12
	global_store_dword v[10:11], v6, off offset:64
.LBB0_1362:
	s_or_b64 exec, exec, s[0:1]
	v_mul_f32_e32 v6, v40, v0
	s_waitcnt lgkmcnt(0)
	s_nop 1
	v_mov_b32_dpp v12, v6 quad_perm:[1,0,3,2] row_mask:0xf bank_mask:0xf
	s_and_saveexec_b64 s[0:1], s[34:35]
	s_cbranch_execz .LBB0_1364
	s_waitcnt lgkmcnt(0)
	v_cvt_pk_bf16_f32 v6, v6, v12
	global_store_dword v[10:11], v6, off offset:128
.LBB0_1364:
	s_or_b64 exec, exec, s[0:1]
	v_mul_f32_e32 v0, v24, v0
	s_nop 1
	v_mov_b32_dpp v6, v0 quad_perm:[1,0,3,2] row_mask:0xf bank_mask:0xf
	s_and_saveexec_b64 s[0:1], s[34:35]
	s_cbranch_execz .LBB0_1366
	s_waitcnt lgkmcnt(0)
	v_cvt_pk_bf16_f32 v0, v0, v6
	global_store_dword v[10:11], v0, off offset:192
.LBB0_1366:
	s_or_b64 exec, exec, s[0:1]
	v_div_scale_f32 v0, s[0:1], v7, v7, 1.0
	s_waitcnt lgkmcnt(0)
	v_rcp_f32_e32 v6, v0
	v_div_scale_f32 v10, vcc, 1.0, v7, 1.0
	s_movk_i32 s0, 0xc00
	v_fma_f32 v11, -v0, v6, 1.0
	v_fmac_f32_e32 v6, v11, v6
	v_mul_f32_e32 v11, v10, v6
	v_fma_f32 v12, -v0, v11, v10
	v_fmac_f32_e32 v11, v12, v6
	v_fma_f32 v0, -v0, v11, v10
	v_div_fmas_f32 v0, v0, v6, v11
	v_div_fixup_f32 v0, v0, v7, 1.0
	v_mul_f32_e32 v10, v73, v0
	s_nop 1
	v_mov_b32_dpp v11, v10 quad_perm:[1,0,3,2] row_mask:0xf bank_mask:0xf
	v_add_u32_e32 v6, 17, v86
	v_mad_i64_i32 v[6:7], s[0:1], v6, s0, v[14:15]
	s_and_saveexec_b64 s[0:1], s[34:35]
	s_cbranch_execz .LBB0_1368
	s_waitcnt lgkmcnt(0)
	v_cvt_pk_bf16_f32 v10, v10, v11
	global_store_dword v[6:7], v10, off
.LBB0_1368:
	s_or_b64 exec, exec, s[0:1]
	v_mul_f32_e32 v10, v57, v0
	s_waitcnt lgkmcnt(0)
	s_nop 1
	v_mov_b32_dpp v11, v10 quad_perm:[1,0,3,2] row_mask:0xf bank_mask:0xf
	s_and_saveexec_b64 s[0:1], s[34:35]
	s_cbranch_execz .LBB0_1370
	s_waitcnt lgkmcnt(0)
	v_cvt_pk_bf16_f32 v10, v10, v11
	global_store_dword v[6:7], v10, off offset:64
.LBB0_1370:
	s_or_b64 exec, exec, s[0:1]
	v_mul_f32_e32 v10, v41, v0
	s_waitcnt lgkmcnt(0)
	s_nop 1
	v_mov_b32_dpp v11, v10 quad_perm:[1,0,3,2] row_mask:0xf bank_mask:0xf
	s_and_saveexec_b64 s[0:1], s[34:35]
	s_cbranch_execz .LBB0_1372
	s_waitcnt lgkmcnt(0)
	v_cvt_pk_bf16_f32 v10, v10, v11
	global_store_dword v[6:7], v10, off offset:128
.LBB0_1372:
	s_or_b64 exec, exec, s[0:1]
	v_mul_f32_e32 v0, v25, v0
	s_nop 1
	v_mov_b32_dpp v10, v0 quad_perm:[1,0,3,2] row_mask:0xf bank_mask:0xf
	s_and_saveexec_b64 s[0:1], s[34:35]
	s_cbranch_execz .LBB0_1374
	s_waitcnt lgkmcnt(0)
	v_cvt_pk_bf16_f32 v0, v0, v10
	global_store_dword v[6:7], v0, off offset:192
.LBB0_1374:
	s_or_b64 exec, exec, s[0:1]
	v_div_scale_f32 v0, s[0:1], v8, v8, 1.0
	v_rcp_f32_e32 v6, v0
	v_div_scale_f32 v7, vcc, 1.0, v8, 1.0
	s_movk_i32 s0, 0xc00
	s_waitcnt lgkmcnt(0)
	v_fma_f32 v10, -v0, v6, 1.0
	v_fmac_f32_e32 v6, v10, v6
	v_mul_f32_e32 v10, v7, v6
	v_fma_f32 v11, -v0, v10, v7
	v_fmac_f32_e32 v10, v11, v6
	v_fma_f32 v0, -v0, v10, v7
	v_div_fmas_f32 v0, v0, v6, v10
	v_div_fixup_f32 v0, v0, v8, 1.0
	v_mul_f32_e32 v8, v74, v0
	s_nop 1
	v_mov_b32_dpp v10, v8 quad_perm:[1,0,3,2] row_mask:0xf bank_mask:0xf
	v_add_u32_e32 v6, 18, v86
	v_mad_i64_i32 v[6:7], s[0:1], v6, s0, v[14:15]
	s_and_saveexec_b64 s[0:1], s[34:35]
	s_cbranch_execz .LBB0_1376
	s_waitcnt lgkmcnt(0)
	v_cvt_pk_bf16_f32 v8, v8, v10
	global_store_dword v[6:7], v8, off
.LBB0_1376:
	s_or_b64 exec, exec, s[0:1]
	v_mul_f32_e32 v8, v58, v0
	s_waitcnt lgkmcnt(0)
	s_nop 1
	v_mov_b32_dpp v10, v8 quad_perm:[1,0,3,2] row_mask:0xf bank_mask:0xf
	s_and_saveexec_b64 s[0:1], s[34:35]
	s_cbranch_execz .LBB0_1378
	s_waitcnt lgkmcnt(0)
	v_cvt_pk_bf16_f32 v8, v8, v10
	global_store_dword v[6:7], v8, off offset:64
.LBB0_1378:
	s_or_b64 exec, exec, s[0:1]
	v_mul_f32_e32 v8, v42, v0
	s_waitcnt lgkmcnt(0)
	s_nop 1
	v_mov_b32_dpp v10, v8 quad_perm:[1,0,3,2] row_mask:0xf bank_mask:0xf
	s_and_saveexec_b64 s[0:1], s[34:35]
	s_cbranch_execz .LBB0_1380
	s_waitcnt lgkmcnt(0)
	v_cvt_pk_bf16_f32 v8, v8, v10
	global_store_dword v[6:7], v8, off offset:128
.LBB0_1380:
	s_or_b64 exec, exec, s[0:1]
	v_mul_f32_e32 v0, v26, v0
	s_nop 1
	v_mov_b32_dpp v8, v0 quad_perm:[1,0,3,2] row_mask:0xf bank_mask:0xf
	s_and_saveexec_b64 s[0:1], s[34:35]
	s_cbranch_execz .LBB0_1382
	s_waitcnt lgkmcnt(0)
	v_cvt_pk_bf16_f32 v0, v0, v8
	global_store_dword v[6:7], v0, off offset:192
.LBB0_1382:
	s_or_b64 exec, exec, s[0:1]
	v_div_scale_f32 v0, s[0:1], v9, v9, 1.0
	v_rcp_f32_e32 v6, v0
	v_div_scale_f32 v7, vcc, 1.0, v9, 1.0
	s_movk_i32 s0, 0xc00
	s_waitcnt lgkmcnt(0)
	v_fma_f32 v8, -v0, v6, 1.0
	v_fmac_f32_e32 v6, v8, v6
	v_mul_f32_e32 v8, v7, v6
	v_fma_f32 v10, -v0, v8, v7
	v_fmac_f32_e32 v8, v10, v6
	v_fma_f32 v0, -v0, v8, v7
	v_div_fmas_f32 v0, v0, v6, v8
	v_div_fixup_f32 v0, v0, v9, 1.0
	v_mul_f32_e32 v8, v75, v0
	s_nop 1
	v_mov_b32_dpp v9, v8 quad_perm:[1,0,3,2] row_mask:0xf bank_mask:0xf
	v_add_u32_e32 v6, 19, v86
	v_mad_i64_i32 v[6:7], s[0:1], v6, s0, v[14:15]
	s_and_saveexec_b64 s[0:1], s[34:35]
	s_cbranch_execz .LBB0_1384
	s_waitcnt lgkmcnt(0)
	v_cvt_pk_bf16_f32 v8, v8, v9
	global_store_dword v[6:7], v8, off
.LBB0_1384:
	s_or_b64 exec, exec, s[0:1]
	v_mul_f32_e32 v8, v59, v0
	s_waitcnt lgkmcnt(0)
	s_nop 1
	v_mov_b32_dpp v9, v8 quad_perm:[1,0,3,2] row_mask:0xf bank_mask:0xf
	s_and_saveexec_b64 s[0:1], s[34:35]
	s_cbranch_execz .LBB0_1386
	s_waitcnt lgkmcnt(0)
	v_cvt_pk_bf16_f32 v8, v8, v9
	global_store_dword v[6:7], v8, off offset:64
.LBB0_1386:
	s_or_b64 exec, exec, s[0:1]
	v_mul_f32_e32 v8, v43, v0
	s_waitcnt lgkmcnt(0)
	s_nop 1
	v_mov_b32_dpp v9, v8 quad_perm:[1,0,3,2] row_mask:0xf bank_mask:0xf
	s_and_saveexec_b64 s[0:1], s[34:35]
	s_cbranch_execz .LBB0_1388
	s_waitcnt lgkmcnt(0)
	v_cvt_pk_bf16_f32 v8, v8, v9
	global_store_dword v[6:7], v8, off offset:128
.LBB0_1388:
	s_or_b64 exec, exec, s[0:1]
	v_mul_f32_e32 v0, v27, v0
	s_nop 1
	v_mov_b32_dpp v8, v0 quad_perm:[1,0,3,2] row_mask:0xf bank_mask:0xf
	s_and_saveexec_b64 s[0:1], s[34:35]
	s_cbranch_execz .LBB0_1390
	s_waitcnt lgkmcnt(0)
	v_cvt_pk_bf16_f32 v0, v0, v8
	global_store_dword v[6:7], v0, off offset:192
.LBB0_1390:
	s_or_b64 exec, exec, s[0:1]
	v_div_scale_f32 v0, s[0:1], v2, v2, 1.0
	v_rcp_f32_e32 v6, v0
	v_div_scale_f32 v7, vcc, 1.0, v2, 1.0
	s_movk_i32 s0, 0xc00
	s_waitcnt lgkmcnt(0)
	v_fma_f32 v8, -v0, v6, 1.0
	v_fmac_f32_e32 v6, v8, v6
	v_mul_f32_e32 v8, v7, v6
	v_fma_f32 v9, -v0, v8, v7
	v_fmac_f32_e32 v8, v9, v6
	v_fma_f32 v0, -v0, v8, v7
	v_div_fmas_f32 v0, v0, v6, v8
	v_div_fixup_f32 v0, v0, v2, 1.0
	v_mul_f32_e32 v2, v76, v0
	s_nop 1
	v_mov_b32_dpp v8, v2 quad_perm:[1,0,3,2] row_mask:0xf bank_mask:0xf
	v_add_u32_e32 v6, 24, v86
	v_mad_i64_i32 v[6:7], s[0:1], v6, s0, v[14:15]
	s_and_saveexec_b64 s[0:1], s[34:35]
	s_cbranch_execz .LBB0_1392
	s_waitcnt lgkmcnt(0)
	v_cvt_pk_bf16_f32 v2, v2, v8
	global_store_dword v[6:7], v2, off
.LBB0_1392:
	s_or_b64 exec, exec, s[0:1]
	v_mul_f32_e32 v2, v60, v0
	s_waitcnt lgkmcnt(0)
	s_nop 1
	v_mov_b32_dpp v8, v2 quad_perm:[1,0,3,2] row_mask:0xf bank_mask:0xf
	s_and_saveexec_b64 s[0:1], s[34:35]
	s_cbranch_execz .LBB0_1394
	s_waitcnt lgkmcnt(0)
	v_cvt_pk_bf16_f32 v2, v2, v8
	global_store_dword v[6:7], v2, off offset:64
.LBB0_1394:
	s_or_b64 exec, exec, s[0:1]
	v_mul_f32_e32 v2, v44, v0
	s_waitcnt lgkmcnt(0)
	s_nop 1
	v_mov_b32_dpp v8, v2 quad_perm:[1,0,3,2] row_mask:0xf bank_mask:0xf
	s_and_saveexec_b64 s[0:1], s[34:35]
	s_cbranch_execz .LBB0_1396
	s_waitcnt lgkmcnt(0)
	v_cvt_pk_bf16_f32 v2, v2, v8
	global_store_dword v[6:7], v2, off offset:128
.LBB0_1396:
	s_or_b64 exec, exec, s[0:1]
	v_mul_f32_e32 v0, v28, v0
	s_nop 1
	v_mov_b32_dpp v2, v0 quad_perm:[1,0,3,2] row_mask:0xf bank_mask:0xf
	s_and_saveexec_b64 s[0:1], s[34:35]
	s_cbranch_execz .LBB0_1398
	s_waitcnt lgkmcnt(0)
	v_cvt_pk_bf16_f32 v0, v0, v2
	global_store_dword v[6:7], v0, off offset:192
.LBB0_1398:
	s_or_b64 exec, exec, s[0:1]
	v_div_scale_f32 v0, s[0:1], v3, v3, 1.0
	s_waitcnt lgkmcnt(0)
	v_rcp_f32_e32 v2, v0
	v_div_scale_f32 v6, vcc, 1.0, v3, 1.0
	s_movk_i32 s0, 0xc00
	v_fma_f32 v7, -v0, v2, 1.0
	v_fmac_f32_e32 v2, v7, v2
	v_mul_f32_e32 v7, v6, v2
	v_fma_f32 v8, -v0, v7, v6
	v_fmac_f32_e32 v7, v8, v2
	v_fma_f32 v0, -v0, v7, v6
	v_div_fmas_f32 v0, v0, v2, v7
	v_div_fixup_f32 v0, v0, v3, 1.0
	v_mul_f32_e32 v6, v77, v0
	s_nop 1
	v_mov_b32_dpp v7, v6 quad_perm:[1,0,3,2] row_mask:0xf bank_mask:0xf
	v_add_u32_e32 v2, 25, v86
	v_mad_i64_i32 v[2:3], s[0:1], v2, s0, v[14:15]
	s_and_saveexec_b64 s[0:1], s[34:35]
	s_cbranch_execz .LBB0_1400
	s_waitcnt lgkmcnt(0)
	v_cvt_pk_bf16_f32 v6, v6, v7
	global_store_dword v[2:3], v6, off
.LBB0_1400:
	s_or_b64 exec, exec, s[0:1]
	v_mul_f32_e32 v6, v61, v0
	s_waitcnt lgkmcnt(0)
	s_nop 1
	v_mov_b32_dpp v7, v6 quad_perm:[1,0,3,2] row_mask:0xf bank_mask:0xf
	s_and_saveexec_b64 s[0:1], s[34:35]
	s_cbranch_execz .LBB0_1402
	s_waitcnt lgkmcnt(0)
	v_cvt_pk_bf16_f32 v6, v6, v7
	global_store_dword v[2:3], v6, off offset:64
.LBB0_1402:
	s_or_b64 exec, exec, s[0:1]
	v_mul_f32_e32 v6, v45, v0
	s_waitcnt lgkmcnt(0)
	s_nop 1
	v_mov_b32_dpp v7, v6 quad_perm:[1,0,3,2] row_mask:0xf bank_mask:0xf
	s_and_saveexec_b64 s[0:1], s[34:35]
	s_cbranch_execz .LBB0_1404
	s_waitcnt lgkmcnt(0)
	v_cvt_pk_bf16_f32 v6, v6, v7
	global_store_dword v[2:3], v6, off offset:128
.LBB0_1404:
	s_or_b64 exec, exec, s[0:1]
	v_mul_f32_e32 v0, v29, v0
	s_nop 1
	v_mov_b32_dpp v6, v0 quad_perm:[1,0,3,2] row_mask:0xf bank_mask:0xf
	s_and_saveexec_b64 s[0:1], s[34:35]
	s_cbranch_execz .LBB0_1406
	s_waitcnt lgkmcnt(0)
	v_cvt_pk_bf16_f32 v0, v0, v6
	global_store_dword v[2:3], v0, off offset:192
.LBB0_1406:
	s_or_b64 exec, exec, s[0:1]
	v_div_scale_f32 v0, s[0:1], v4, v4, 1.0
	v_rcp_f32_e32 v2, v0
	v_div_scale_f32 v3, vcc, 1.0, v4, 1.0
	s_movk_i32 s0, 0xc00
	s_waitcnt lgkmcnt(0)
	v_fma_f32 v6, -v0, v2, 1.0
	v_fmac_f32_e32 v2, v6, v2
	v_mul_f32_e32 v6, v3, v2
	v_fma_f32 v7, -v0, v6, v3
	v_fmac_f32_e32 v6, v7, v2
	v_fma_f32 v0, -v0, v6, v3
	v_div_fmas_f32 v0, v0, v2, v6
	v_div_fixup_f32 v0, v0, v4, 1.0
	v_mul_f32_e32 v4, v78, v0
	s_nop 1
	v_mov_b32_dpp v6, v4 quad_perm:[1,0,3,2] row_mask:0xf bank_mask:0xf
	v_add_u32_e32 v2, 26, v86
	v_mad_i64_i32 v[2:3], s[0:1], v2, s0, v[14:15]
	s_and_saveexec_b64 s[0:1], s[34:35]
	s_cbranch_execz .LBB0_1408
	s_waitcnt lgkmcnt(0)
	v_cvt_pk_bf16_f32 v4, v4, v6
	global_store_dword v[2:3], v4, off
.LBB0_1408:
	s_or_b64 exec, exec, s[0:1]
	v_mul_f32_e32 v4, v62, v0
	s_waitcnt lgkmcnt(0)
	s_nop 1
	v_mov_b32_dpp v6, v4 quad_perm:[1,0,3,2] row_mask:0xf bank_mask:0xf
	s_and_saveexec_b64 s[0:1], s[34:35]
	s_cbranch_execz .LBB0_1410
	s_waitcnt lgkmcnt(0)
	v_cvt_pk_bf16_f32 v4, v4, v6
	global_store_dword v[2:3], v4, off offset:64
.LBB0_1410:
	s_or_b64 exec, exec, s[0:1]
	v_mul_f32_e32 v4, v46, v0
	s_waitcnt lgkmcnt(0)
	s_nop 1
	v_mov_b32_dpp v6, v4 quad_perm:[1,0,3,2] row_mask:0xf bank_mask:0xf
	s_and_saveexec_b64 s[0:1], s[34:35]
	s_cbranch_execz .LBB0_1412
	s_waitcnt lgkmcnt(0)
	v_cvt_pk_bf16_f32 v4, v4, v6
	global_store_dword v[2:3], v4, off offset:128
.LBB0_1412:
	s_or_b64 exec, exec, s[0:1]
	v_mul_f32_e32 v0, v30, v0
	s_nop 1
	v_mov_b32_dpp v4, v0 quad_perm:[1,0,3,2] row_mask:0xf bank_mask:0xf
	s_and_saveexec_b64 s[0:1], s[34:35]
	s_cbranch_execz .LBB0_1414
	s_waitcnt lgkmcnt(0)
	v_cvt_pk_bf16_f32 v0, v0, v4
	global_store_dword v[2:3], v0, off offset:192
.LBB0_1414:
	s_or_b64 exec, exec, s[0:1]
	v_div_scale_f32 v0, s[0:1], v5, v5, 1.0
	v_rcp_f32_e32 v2, v0
	v_div_scale_f32 v3, vcc, 1.0, v5, 1.0
	s_movk_i32 s0, 0xc00
	s_waitcnt lgkmcnt(0)
	v_fma_f32 v4, -v0, v2, 1.0
	v_fmac_f32_e32 v2, v4, v2
	v_mul_f32_e32 v4, v3, v2
	v_fma_f32 v6, -v0, v4, v3
	v_fmac_f32_e32 v4, v6, v2
	v_fma_f32 v0, -v0, v4, v3
	v_div_fmas_f32 v0, v0, v2, v4
	v_div_fixup_f32 v0, v0, v5, 1.0
	v_mul_f32_e32 v4, v79, v0
	s_nop 1
	v_mov_b32_dpp v5, v4 quad_perm:[1,0,3,2] row_mask:0xf bank_mask:0xf
	v_add_u32_e32 v2, 27, v86
	v_mad_i64_i32 v[2:3], s[0:1], v2, s0, v[14:15]
	s_and_saveexec_b64 s[0:1], s[34:35]
	s_cbranch_execz .LBB0_1416
	s_waitcnt lgkmcnt(0)
	v_cvt_pk_bf16_f32 v4, v4, v5
	global_store_dword v[2:3], v4, off
.LBB0_1416:
	s_or_b64 exec, exec, s[0:1]
	v_mul_f32_e32 v4, v63, v0
	s_waitcnt lgkmcnt(0)
	s_nop 1
	v_mov_b32_dpp v5, v4 quad_perm:[1,0,3,2] row_mask:0xf bank_mask:0xf
	s_and_saveexec_b64 s[0:1], s[34:35]
	s_cbranch_execz .LBB0_1418
	s_waitcnt lgkmcnt(0)
	v_cvt_pk_bf16_f32 v4, v4, v5
	global_store_dword v[2:3], v4, off offset:64
.LBB0_1418:
	s_or_b64 exec, exec, s[0:1]
	v_mul_f32_e32 v4, v47, v0
	s_waitcnt lgkmcnt(0)
	s_nop 1
	v_mov_b32_dpp v5, v4 quad_perm:[1,0,3,2] row_mask:0xf bank_mask:0xf
	s_and_saveexec_b64 s[0:1], s[34:35]
	s_cbranch_execz .LBB0_1420
	s_waitcnt lgkmcnt(0)
	v_cvt_pk_bf16_f32 v4, v4, v5
	global_store_dword v[2:3], v4, off offset:128
.LBB0_1420:
	s_or_b64 exec, exec, s[0:1]
	v_mul_f32_e32 v0, v31, v0
	s_nop 1
	v_mov_b32_dpp v4, v0 quad_perm:[1,0,3,2] row_mask:0xf bank_mask:0xf
	s_and_saveexec_b64 s[0:1], s[34:35]
	s_xor_b64 s[0:1], exec, s[0:1]
	s_cbranch_execz .LBB0_1422
	s_waitcnt lgkmcnt(0)
	v_cvt_pk_bf16_f32 v0, v0, v4
	global_store_dword v[2:3], v0, off offset:192

.LBB0_1741:
	v_mov_b32_e32 v130, s30
	ds_read_b32 v130, v130
	v_lshl_add_u32 v156, s25, 8, v170
	s_add_i32 s2, s25, 1
	s_or_b32 s14, s2, s29
	v_or_b32_e32 v154, 16, v156
	s_waitcnt lgkmcnt(0)
	v_readfirstlane_b32 s2, v130
	v_or_b32_e32 v152, 32, v156
	v_or_b32_e32 v150, 48, v156
	s_mov_b64 s[0:1], -1
	s_cmp_eq_u32 s2, s14
	v_ashrrev_i32_e32 v157, 31, v156
	v_ashrrev_i32_e32 v155, 31, v154
	v_ashrrev_i32_e32 v153, 31, v152
	v_ashrrev_i32_e32 v151, 31, v150
	v_add_u32_e32 v160, 0x80, v156
	s_cbranch_scc1 .LBB0_1743
	v_and_b32_e32 v131, 64, v231
	v_xor_b32_e32 v130, 16, v231
	v_add_u32_e32 v131, 64, v131
	v_cmp_lt_i32_e32 vcc, v130, v131
	s_mov_b32 s2, 0xf800000
	s_nop 0
	v_cndmask_b32_e32 v130, v231, v130, vcc
	v_lshlrev_b32_e32 v169, 2, v130
	v_xor_b32_e32 v130, 32, v231
	v_cmp_lt_i32_e32 vcc, v130, v131
	s_nop 1
	v_cndmask_b32_e32 v130, v231, v130, vcc
	v_lshlrev_b32_e32 v161, 2, v130
	v_lshlrev_b64 v[130:131], 7, v[156:157]
	v_lshl_add_u64 v[130:131], v[144:145], 0, v[130:131]
	s_mov_b64 s[0:1], 0x1000
	global_load_dword v182, v[130:131], off offset:2048
	v_lshl_add_u64 v[190:191], v[130:131], 0, s[0:1]
	global_load_dword v183, v[190:191], off
	global_load_dword v184, v[190:191], off offset:2048
	s_mov_b64 s[0:1], 0x4000
	v_lshl_add_u64 v[190:191], v[130:131], 0, s[0:1]
	global_load_dword v185, v[190:191], off
	global_load_dword v186, v[190:191], off offset:2048
	s_mov_b64 s[0:1], 0x5000
	v_lshl_add_u64 v[190:191], v[130:131], 0, s[0:1]
	global_load_dword v187, v[190:191], off
	global_load_dword v188, v[190:191], off offset:2048
	global_load_dwordx4 v[132:135], v[130:131], off
	global_load_dwordx4 v[162:165], v[130:131], off offset:16
	s_waitcnt vmcnt(0)
	v_mov_b32_e32 v136, v132
	v_mov_b32_e32 v137, v162
	v_mov_b32_e32 v162, v133
	v_pk_add_f32 v[132:133], v[136:137], v[162:163]
	v_mov_b32_e32 v136, v134
	v_mov_b32_e32 v137, v164
	v_mov_b32_e32 v164, v135
	v_pk_add_f32 v[134:135], v[136:137], v[164:165]
	s_nop 0
	v_pk_add_f32 v[132:133], v[132:133], v[134:135]
	s_nop 0
	v_add_f32_e32 v132, v132, v133
	ds_bpermute_b32 v133, v169, v132
	s_waitcnt lgkmcnt(0)
	v_add_f32_e32 v132, v132, v133
	ds_bpermute_b32 v133, v161, v132
	s_waitcnt lgkmcnt(0)
	v_add_f32_e32 v132, v132, v133
	v_fmamk_f32 v132, v132, 0x3a000000, v230
	v_cmp_gt_f32_e32 vcc, s2, v132
	v_mul_f32_e32 v133, 0x4f800000, v132
	s_nop 0
	v_cndmask_b32_e32 v132, v132, v133, vcc
	v_sqrt_f32_e32 v133, v132
	s_nop 0
	v_add_u32_e32 v134, -1, v133
	v_fma_f32 v135, -v134, v133, v132
	v_cmp_ge_f32_e64 s[0:1], 0, v135
	v_add_u32_e32 v135, 1, v133
	s_nop 0
	v_cndmask_b32_e64 v134, v133, v134, s[0:1]
	v_fma_f32 v133, -v135, v133, v132
	v_cmp_lt_f32_e64 s[0:1], 0, v133
	s_nop 1
	v_cndmask_b32_e64 v133, v134, v135, s[0:1]
	v_mul_f32_e32 v134, 0x37800000, v133
	v_cndmask_b32_e32 v133, v133, v134, vcc
	v_cmp_class_f32_e32 vcc, v132, v228
	s_nop 1
	v_cndmask_b32_e32 v132, v133, v132, vcc
	v_div_scale_f32 v133, s[0:1], v132, v132, 1.0
	v_rcp_f32_e32 v134, v133
	s_nop 0
	v_fma_f32 v135, -v133, v134, 1.0
	v_fmac_f32_e32 v134, v135, v134
	v_div_scale_f32 v135, vcc, 1.0, v132, 1.0
	v_mul_f32_e32 v136, v135, v134
	v_fma_f32 v137, -v133, v136, v135
	v_fmac_f32_e32 v136, v137, v134
	v_fma_f32 v133, -v133, v136, v135
	v_div_fmas_f32 v133, v133, v134, v136
	v_div_fixup_f32 v158, v133, v132, 1.0
	v_lshlrev_b64 v[132:133], 7, v[154:155]
	v_lshl_add_u64 v[136:137], v[144:145], 0, v[132:133]
	global_load_dwordx4 v[132:135], v[136:137], off
	global_load_dwordx4 v[162:165], v[136:137], off offset:16
	s_waitcnt vmcnt(1)
	v_mov_b32_e32 v136, v132
	s_waitcnt vmcnt(0)
	v_mov_b32_e32 v137, v162
	v_mov_b32_e32 v162, v133
	v_pk_add_f32 v[132:133], v[136:137], v[162:163]
	v_mov_b32_e32 v136, v134
	v_mov_b32_e32 v137, v164
	v_mov_b32_e32 v164, v135
	v_pk_add_f32 v[134:135], v[136:137], v[164:165]
	s_nop 0
	v_pk_add_f32 v[132:133], v[132:133], v[134:135]
	s_nop 0
	v_add_f32_e32 v132, v132, v133
	ds_bpermute_b32 v133, v169, v132
	s_waitcnt lgkmcnt(0)
	v_add_f32_e32 v132, v132, v133
	ds_bpermute_b32 v133, v161, v132
	s_waitcnt lgkmcnt(0)
	v_add_f32_e32 v132, v132, v133
	v_fmamk_f32 v132, v132, 0x3a000000, v230
	v_cmp_gt_f32_e32 vcc, s2, v132
	v_mul_f32_e32 v133, 0x4f800000, v132
	s_nop 0
	v_cndmask_b32_e32 v132, v132, v133, vcc
	v_sqrt_f32_e32 v133, v132
	s_nop 0
	v_add_u32_e32 v134, -1, v133
	v_fma_f32 v135, -v134, v133, v132
	v_cmp_ge_f32_e64 s[0:1], 0, v135
	v_add_u32_e32 v135, 1, v133
	s_nop 0
	v_cndmask_b32_e64 v134, v133, v134, s[0:1]
	v_fma_f32 v133, -v135, v133, v132
	v_cmp_lt_f32_e64 s[0:1], 0, v133
	s_nop 1
	v_cndmask_b32_e64 v133, v134, v135, s[0:1]
	v_mul_f32_e32 v134, 0x37800000, v133
	v_cndmask_b32_e32 v133, v133, v134, vcc
	v_cmp_class_f32_e32 vcc, v132, v228
	s_nop 1
	v_cndmask_b32_e32 v132, v133, v132, vcc
	v_div_scale_f32 v133, s[0:1], v132, v132, 1.0
	v_rcp_f32_e32 v134, v133
	s_nop 0
	v_fma_f32 v135, -v133, v134, 1.0
	v_fmac_f32_e32 v134, v135, v134
	v_div_scale_f32 v135, vcc, 1.0, v132, 1.0
	v_mul_f32_e32 v136, v135, v134
	v_fma_f32 v137, -v133, v136, v135
	v_fmac_f32_e32 v136, v137, v134
	v_fma_f32 v133, -v133, v136, v135
	v_div_fmas_f32 v133, v133, v134, v136
	v_div_fixup_f32 v159, v133, v132, 1.0
	v_lshlrev_b64 v[132:133], 7, v[152:153]
	ds_write2_b32 v173, v158, v159 offset1:16
	v_lshl_add_u64 v[136:137], v[144:145], 0, v[132:133]
	global_load_dwordx4 v[132:135], v[136:137], off
	global_load_dwordx4 v[162:165], v[136:137], off offset:16
	s_waitcnt vmcnt(1)
	v_mov_b32_e32 v136, v132
	s_waitcnt vmcnt(0)
	v_mov_b32_e32 v137, v162
	v_mov_b32_e32 v162, v133
	v_pk_add_f32 v[132:133], v[136:137], v[162:163]
	v_mov_b32_e32 v136, v134
	v_mov_b32_e32 v137, v164
	v_mov_b32_e32 v164, v135
	v_pk_add_f32 v[134:135], v[136:137], v[164:165]
	s_nop 0
	v_pk_add_f32 v[132:133], v[132:133], v[134:135]
	s_nop 0
	v_add_f32_e32 v132, v132, v133
	ds_bpermute_b32 v133, v169, v132
	s_waitcnt lgkmcnt(0)
	v_add_f32_e32 v132, v132, v133
	ds_bpermute_b32 v133, v161, v132
	s_waitcnt lgkmcnt(0)
	v_add_f32_e32 v132, v132, v133
	v_fmamk_f32 v132, v132, 0x3a000000, v230
	v_cmp_gt_f32_e32 vcc, s2, v132
	v_mul_f32_e32 v133, 0x4f800000, v132
	s_nop 0
	v_cndmask_b32_e32 v132, v132, v133, vcc
	v_sqrt_f32_e32 v133, v132
	s_nop 0
	v_add_u32_e32 v134, -1, v133
	v_fma_f32 v135, -v134, v133, v132
	v_cmp_ge_f32_e64 s[0:1], 0, v135
	v_add_u32_e32 v135, 1, v133
	s_nop 0
	v_cndmask_b32_e64 v134, v133, v134, s[0:1]
	v_fma_f32 v133, -v135, v133, v132
	v_cmp_lt_f32_e64 s[0:1], 0, v133
	s_nop 1
	v_cndmask_b32_e64 v133, v134, v135, s[0:1]
	v_mul_f32_e32 v134, 0x37800000, v133
	v_cndmask_b32_e32 v133, v133, v134, vcc
	v_cmp_class_f32_e32 vcc, v132, v228
	s_nop 1
	v_cndmask_b32_e32 v132, v133, v132, vcc
	v_div_scale_f32 v133, s[0:1], v132, v132, 1.0
	v_rcp_f32_e32 v134, v133
	s_nop 0
	v_fma_f32 v135, -v133, v134, 1.0
	v_fmac_f32_e32 v134, v135, v134
	v_div_scale_f32 v135, vcc, 1.0, v132, 1.0
	v_mul_f32_e32 v136, v135, v134
	v_fma_f32 v137, -v133, v136, v135
	v_fmac_f32_e32 v136, v137, v134
	v_fma_f32 v133, -v133, v136, v135
	v_div_fmas_f32 v133, v133, v134, v136
	v_div_fixup_f32 v162, v133, v132, 1.0
	v_lshlrev_b64 v[132:133], 7, v[150:151]
	v_lshl_add_u64 v[136:137], v[144:145], 0, v[132:133]
	global_load_dwordx4 v[132:135], v[136:137], off
	global_load_dwordx4 v[164:167], v[136:137], off offset:16
	s_waitcnt vmcnt(1)
	v_mov_b32_e32 v136, v132
	s_waitcnt vmcnt(0)
	v_mov_b32_e32 v137, v164
	v_mov_b32_e32 v164, v133
	v_pk_add_f32 v[132:133], v[136:137], v[164:165]
	v_mov_b32_e32 v136, v134
	v_mov_b32_e32 v137, v166
	v_mov_b32_e32 v166, v135
	v_pk_add_f32 v[134:135], v[136:137], v[166:167]
	v_add_u32_e32 v164, 0x80, v156
	v_pk_add_f32 v[132:133], v[132:133], v[134:135]
	v_ashrrev_i32_e32 v165, 31, v164
	v_add_f32_e32 v132, v132, v133
	ds_bpermute_b32 v133, v169, v132
	s_waitcnt lgkmcnt(0)
	v_add_f32_e32 v132, v132, v133
	ds_bpermute_b32 v133, v161, v132
	s_waitcnt lgkmcnt(0)
	v_add_f32_e32 v132, v132, v133
	v_fmamk_f32 v132, v132, 0x3a000000, v230
	v_cmp_gt_f32_e32 vcc, s2, v132
	v_mul_f32_e32 v133, 0x4f800000, v132
	s_nop 0
	v_cndmask_b32_e32 v132, v132, v133, vcc
	v_sqrt_f32_e32 v133, v132
	s_nop 0
	v_add_u32_e32 v134, -1, v133
	v_fma_f32 v135, -v134, v133, v132
	v_cmp_ge_f32_e64 s[0:1], 0, v135
	v_add_u32_e32 v135, 1, v133
	s_nop 0
	v_cndmask_b32_e64 v134, v133, v134, s[0:1]
	v_fma_f32 v133, -v135, v133, v132
	v_cmp_lt_f32_e64 s[0:1], 0, v133
	s_nop 1
	v_cndmask_b32_e64 v133, v134, v135, s[0:1]
	v_mul_f32_e32 v134, 0x37800000, v133
	v_cndmask_b32_e32 v133, v133, v134, vcc
	v_cmp_class_f32_e32 vcc, v132, v228
	s_nop 1
	v_cndmask_b32_e32 v132, v133, v132, vcc
	v_div_scale_f32 v133, s[0:1], v132, v132, 1.0
	v_rcp_f32_e32 v134, v133
	s_nop 0
	v_fma_f32 v135, -v133, v134, 1.0
	v_fmac_f32_e32 v134, v135, v134
	v_div_scale_f32 v135, vcc, 1.0, v132, 1.0
	v_mul_f32_e32 v136, v135, v134
	v_fma_f32 v137, -v133, v136, v135
	v_fmac_f32_e32 v136, v137, v134
	v_fma_f32 v133, -v133, v136, v135
	v_div_fmas_f32 v133, v133, v134, v136
	v_div_fixup_f32 v163, v133, v132, 1.0
	v_lshlrev_b64 v[132:133], 7, v[164:165]
	ds_write2_b32 v173, v162, v163 offset0:32 offset1:48
	v_lshl_add_u64 v[136:137], v[144:145], 0, v[132:133]
	global_load_dwordx4 v[132:135], v[136:137], off
	global_load_dwordx4 v[176:179], v[136:137], off offset:16
	s_waitcnt vmcnt(1)
	v_mov_b32_e32 v136, v132
	s_waitcnt vmcnt(0)
	v_mov_b32_e32 v137, v176
	v_mov_b32_e32 v176, v133
	v_pk_add_f32 v[132:133], v[136:137], v[176:177]
	v_mov_b32_e32 v136, v134
	v_mov_b32_e32 v137, v178
	v_mov_b32_e32 v178, v135
	v_pk_add_f32 v[134:135], v[136:137], v[178:179]
	s_nop 0
	v_pk_add_f32 v[132:133], v[132:133], v[134:135]
	s_nop 0
	v_add_f32_e32 v132, v132, v133
	ds_bpermute_b32 v133, v169, v132
	s_waitcnt lgkmcnt(0)
	v_add_f32_e32 v132, v132, v133
	ds_bpermute_b32 v133, v161, v132
	s_waitcnt lgkmcnt(0)
	v_add_f32_e32 v132, v132, v133
	v_fmamk_f32 v132, v132, 0x3a000000, v230
	v_cmp_gt_f32_e32 vcc, s2, v132
	v_mul_f32_e32 v133, 0x4f800000, v132
	s_nop 0
	v_cndmask_b32_e32 v132, v132, v133, vcc
	v_sqrt_f32_e32 v133, v132
	s_nop 0
	v_add_u32_e32 v134, -1, v133
	v_fma_f32 v135, -v134, v133, v132
	v_cmp_ge_f32_e64 s[0:1], 0, v135
	v_add_u32_e32 v135, 1, v133
	s_nop 0
	v_cndmask_b32_e64 v134, v133, v134, s[0:1]
	v_fma_f32 v133, -v135, v133, v132
	v_cmp_lt_f32_e64 s[0:1], 0, v133
	s_nop 1
	v_cndmask_b32_e64 v133, v134, v135, s[0:1]
	v_mul_f32_e32 v134, 0x37800000, v133
	v_cndmask_b32_e32 v133, v133, v134, vcc
	v_cmp_class_f32_e32 vcc, v132, v228
	s_nop 1
	v_cndmask_b32_e32 v132, v133, v132, vcc
	v_div_scale_f32 v133, s[0:1], v132, v132, 1.0
	v_rcp_f32_e32 v134, v133
	s_mov_b64 s[0:1], 0x4800
	v_fma_f32 v135, -v133, v134, 1.0
	v_fmac_f32_e32 v134, v135, v134
	v_div_scale_f32 v135, vcc, 1.0, v132, 1.0
	v_mul_f32_e32 v136, v135, v134
	v_fma_f32 v137, -v133, v136, v135
	v_fmac_f32_e32 v136, v137, v134
	v_fma_f32 v133, -v133, v136, v135
	v_div_fmas_f32 v133, v133, v134, v136
	v_lshl_add_u64 v[136:137], v[130:131], 0, s[0:1]
	s_movk_i32 s0, 0x4000
	v_div_fixup_f32 v166, v133, v132, 1.0
	v_add_co_u32_e32 v132, vcc, s0, v130
	s_nop 1
	v_addc_co_u32_e32 v133, vcc, 0, v131, vcc
	global_load_dwordx4 v[132:135], v[132:133], off offset:2048
	s_nop 0
	global_load_dwordx4 v[176:179], v[136:137], off offset:16
	s_waitcnt vmcnt(1)
	v_mov_b32_e32 v136, v132
	s_waitcnt vmcnt(0)
	v_mov_b32_e32 v137, v176
	v_mov_b32_e32 v176, v133
	v_pk_add_f32 v[132:133], v[136:137], v[176:177]
	v_mov_b32_e32 v136, v134
	v_mov_b32_e32 v137, v178
	v_mov_b32_e32 v178, v135
	v_pk_add_f32 v[134:135], v[136:137], v[178:179]
	s_nop 0
	v_pk_add_f32 v[132:133], v[132:133], v[134:135]
	s_nop 0
	v_add_f32_e32 v132, v132, v133
	ds_bpermute_b32 v133, v169, v132
	s_waitcnt lgkmcnt(0)
	v_add_f32_e32 v132, v132, v133
	ds_bpermute_b32 v133, v161, v132
	s_waitcnt lgkmcnt(0)
	v_add_f32_e32 v132, v132, v133
	v_fmamk_f32 v132, v132, 0x3a000000, v230
	v_cmp_gt_f32_e32 vcc, s2, v132
	v_mul_f32_e32 v133, 0x4f800000, v132
	s_nop 0
	v_cndmask_b32_e32 v132, v132, v133, vcc
	v_sqrt_f32_e32 v133, v132
	s_nop 0
	v_add_u32_e32 v134, -1, v133
	v_fma_f32 v135, -v134, v133, v132
	v_cmp_ge_f32_e64 s[0:1], 0, v135
	v_add_u32_e32 v135, 1, v133
	s_nop 0
	v_cndmask_b32_e64 v134, v133, v134, s[0:1]
	v_fma_f32 v133, -v135, v133, v132
	v_cmp_lt_f32_e64 s[0:1], 0, v133
	s_nop 1
	v_cndmask_b32_e64 v133, v134, v135, s[0:1]
	v_mul_f32_e32 v134, 0x37800000, v133
	v_cndmask_b32_e32 v133, v133, v134, vcc
	v_cmp_class_f32_e32 vcc, v132, v228
	s_nop 1
	v_cndmask_b32_e32 v132, v133, v132, vcc
	v_div_scale_f32 v133, s[0:1], v132, v132, 1.0
	v_rcp_f32_e32 v134, v133
	s_mov_b64 s[0:1], 0x5000
	v_lshl_add_u64 v[176:177], v[130:131], 0, s[0:1]
	s_movk_i32 s0, 0x5000
	v_fma_f32 v135, -v133, v134, 1.0
	v_fmac_f32_e32 v134, v135, v134
	v_div_scale_f32 v135, vcc, 1.0, v132, 1.0
	v_mul_f32_e32 v136, v135, v134
	v_fma_f32 v137, -v133, v136, v135
	v_fmac_f32_e32 v136, v137, v134
	v_fma_f32 v133, -v133, v136, v135
	v_div_fmas_f32 v133, v133, v134, v136
	v_div_fixup_f32 v167, v133, v132, 1.0
	v_add_co_u32_e32 v132, vcc, s0, v130
	ds_write2_b32 v173, v166, v167 offset0:64 offset1:80
	s_nop 0
	v_addc_co_u32_e32 v133, vcc, 0, v131, vcc
	global_load_dwordx4 v[134:137], v[132:133], off
	s_nop 0
	global_load_dwordx4 v[176:179], v[176:177], off offset:16
	s_waitcnt vmcnt(1)
	v_mov_b32_e32 v180, v134
	s_waitcnt vmcnt(0)
	v_mov_b32_e32 v181, v176
	v_mov_b32_e32 v176, v135
	v_pk_add_f32 v[134:135], v[180:181], v[176:177]
	v_mov_b32_e32 v176, v136
	v_mov_b32_e32 v177, v178
	v_mov_b32_e32 v178, v137
	v_pk_add_f32 v[136:137], v[176:177], v[178:179]
	s_nop 0
	v_pk_add_f32 v[134:135], v[134:135], v[136:137]
	s_nop 0
	v_add_f32_e32 v134, v134, v135
	ds_bpermute_b32 v135, v169, v134
	s_waitcnt lgkmcnt(0)
	v_add_f32_e32 v134, v134, v135
	ds_bpermute_b32 v135, v161, v134
	s_waitcnt lgkmcnt(0)
	v_add_f32_e32 v134, v134, v135
	v_fmamk_f32 v134, v134, 0x3a000000, v230
	v_cmp_gt_f32_e32 vcc, s2, v134
	v_mul_f32_e32 v135, 0x4f800000, v134
	s_nop 0
	v_cndmask_b32_e32 v134, v134, v135, vcc
	v_sqrt_f32_e32 v135, v134
	s_nop 0
	v_add_u32_e32 v136, -1, v135
	v_fma_f32 v137, -v136, v135, v134
	v_cmp_ge_f32_e64 s[0:1], 0, v137
	v_add_u32_e32 v137, 1, v135
	s_nop 0
	v_cndmask_b32_e64 v136, v135, v136, s[0:1]
	v_fma_f32 v135, -v137, v135, v134
	v_cmp_lt_f32_e64 s[0:1], 0, v135
	s_nop 1
	v_cndmask_b32_e64 v135, v136, v137, s[0:1]
	v_mul_f32_e32 v136, 0x37800000, v135
	v_cndmask_b32_e32 v135, v135, v136, vcc
	v_cmp_class_f32_e32 vcc, v134, v228
	s_nop 1
	v_cndmask_b32_e32 v134, v135, v134, vcc
	v_div_scale_f32 v135, s[0:1], v134, v134, 1.0
	v_rcp_f32_e32 v136, v135
	s_mov_b64 s[0:1], 0x5800
	v_lshl_add_u64 v[130:131], v[130:131], 0, s[0:1]
	v_fma_f32 v137, -v135, v136, 1.0
	v_fmac_f32_e32 v136, v137, v136
	v_div_scale_f32 v137, vcc, 1.0, v134, 1.0
	v_mul_f32_e32 v168, v137, v136
	v_fma_f32 v175, -v135, v168, v137
	v_fmac_f32_e32 v168, v175, v136
	v_fma_f32 v135, -v135, v168, v137
	v_div_fmas_f32 v135, v135, v136, v168
	v_div_fixup_f32 v168, v135, v134, 1.0
	global_load_dwordx4 v[134:137], v[132:133], off offset:2048
	s_nop 0
	global_load_dwordx4 v[130:133], v[130:131], off offset:16
	s_waitcnt vmcnt(1)
	v_mov_b32_e32 v176, v134
	s_waitcnt vmcnt(0)
	v_mov_b32_e32 v177, v130
	v_mov_b32_e32 v130, v135
	v_mov_b32_e32 v134, v136
	v_mov_b32_e32 v135, v132
	v_mov_b32_e32 v132, v137
	v_pk_add_f32 v[130:131], v[176:177], v[130:131]
	v_pk_add_f32 v[132:133], v[134:135], v[132:133]
	s_nop 0
	v_pk_add_f32 v[130:131], v[130:131], v[132:133]
	s_nop 0
	v_add_f32_e32 v130, v130, v131
	ds_bpermute_b32 v131, v169, v130
	s_waitcnt lgkmcnt(0)
	v_add_f32_e32 v130, v130, v131
	ds_bpermute_b32 v131, v161, v130
	s_waitcnt lgkmcnt(0)
	v_add_f32_e32 v130, v130, v131
	v_fmamk_f32 v130, v130, 0x3a000000, v230
	v_cmp_gt_f32_e32 vcc, s2, v130
	v_mul_f32_e32 v131, 0x4f800000, v130
	s_nop 0
	v_cndmask_b32_e32 v130, v130, v131, vcc
	v_sqrt_f32_e32 v131, v130
	s_nop 0
	v_add_u32_e32 v132, -1, v131
	v_fma_f32 v133, -v132, v131, v130
	v_cmp_ge_f32_e64 s[0:1], 0, v133
	v_add_u32_e32 v133, 1, v131
	s_nop 0
	v_cndmask_b32_e64 v132, v131, v132, s[0:1]
	v_fma_f32 v131, -v133, v131, v130
	v_cmp_lt_f32_e64 s[0:1], 0, v131
	s_nop 1
	v_cndmask_b32_e64 v131, v132, v133, s[0:1]
	v_mul_f32_e32 v132, 0x37800000, v131
	v_cndmask_b32_e32 v131, v131, v132, vcc
	v_cmp_class_f32_e32 vcc, v130, v228
	s_nop 1
	v_cndmask_b32_e32 v130, v131, v130, vcc
	v_div_scale_f32 v131, s[0:1], v130, v130, 1.0
	v_rcp_f32_e32 v132, v131
	s_mov_b64 s[0:1], 0
	v_fma_f32 v133, -v131, v132, 1.0
	v_fmac_f32_e32 v132, v133, v132
	v_div_scale_f32 v133, vcc, 1.0, v130, 1.0
	v_mul_f32_e32 v134, v133, v132
	v_fma_f32 v135, -v131, v134, v133
	v_fmac_f32_e32 v134, v135, v132
	v_fma_f32 v131, -v131, v134, v133
	v_div_fmas_f32 v131, v131, v132, v134
	v_div_fixup_f32 v169, v131, v130, 1.0
	v_mov_b32_e32 v130, s30
	v_mov_b32_e32 v131, s14
	ds_write2_b32 v173, v168, v169 offset0:96 offset1:112
	ds_write_b32 v130, v131
	v_mov_b64_e32 v[130:131], v[164:165]
